# MFMA/VALU overlap across wave halves: wr==0 half's epilogue-alignment barrier moved into its epilogue (P1/P3/P7) so its epilogue VALU starts under the other half's last MFMA phase
# speedup vs baseline: 1.0048x; 1.0048x over previous
; template <int NP> __device__ __forceinline__ void load_rs(const float* ssp, int row0, int fq, float (&rs)[2][4]) {
;     if (NP == 1) {
; #pragma unroll
;         for (int ai = 0; ai < 2; ++ai)
; #pragma unroll
;             for (int m = 0; m < 4; ++m) rs[ai][m] = ssp[row0 + ai * HALF + m * 16];
;     } else {
;         f32x4 p[2][4];
; #pragma unroll
;         for (int ai = 0; ai < 2; ++ai)
; #pragma unroll
;             for (int m = 0; m < 4; ++m) p[ai][m] = *(const f32x4*)(ssp + (size_t)(row0 + ai * HALF + m * 16) * 16 + 4 * fq);
; #pragma unroll
;         for (int ai = 0; ai < 2; ++ai)
; #pragma unroll
;             for (int m = 0; m < 4; ++m) { float s = (p[ai][m][0] + p[ai][m][1]) + (p[ai][m][2] + p[ai][m][3]); s += __shfl_xor(s, 16); s += __shfl_xor(s, 32); rs[ai][m] = s; }
;     }
; #pragma unroll
;     for (int ai = 0; ai < 2; ++ai)
; #pragma unroll
;     __device__ __forceinline__ void operator()(const f32x4 (&acc)[2][2][4][2], const Unit& u, int wr, int wc, int fr, int fq) const {
;         const int row0 = u.pm * BM + wr * 64 + fr, col0 = u.pn * HALF + wc * 32 + 8 * fq;
;         float rs[2][4]; load_rs<NP>(ssp, row0, fq, rs);
; #pragma unroll
;         for (int ai = 0; ai < 2; ++ai)
; #pragma unroll
;             for (int m = 0; m < 4; ++m) {
;                 const int row = row0 + ai * HALF + m * 16; const float r = rs[ai][m];
;                 const float nrl = r * -1.44269504089f, r2 = r * r;
;                 unsigned pk[4];
; #pragma unroll
;                 for (int q = 0; q < 4; ++q) {
;                     const f32x4 ga = acc[ai][0][m][q >> 1], ua = acc[ai][1][m][q >> 1]; const int e0 = 2 * (q & 1);
;                     const f32x2 g = (f32x2){ga[e0], ga[e0 + 1]}, up = (f32x2){ua[e0], ua[e0 + 1]};
;                     const f32x2 t = g * nrl; f32x2 ex; ex.x = __builtin_amdgcn_exp2f(t.x); ex.y = __builtin_amdgcn_exp2f(t.y);
;                     const f32x2 d = ex + 1.0f; f32x2 rc; rc.x = __builtin_amdgcn_rcpf(d.x); rc.y = __builtin_amdgcn_rcpf(d.y);
;                     const f32x2 o = (g * up) * (rc * r2);
;                     pk[q] = cvt_pk_bf16(o.x, o.y);
;                 }
;                 u32x4 w; w.x = pk[0]; w.y = pk[1]; w.z = pk[2]; w.w = pk[3];
;                 *(u32x4*)(U + (size_t)(row >> 13) * U_SLAB + (size_t)(row & (SEQ - 1)) * U_PITCH + col0) = w;
.LBB0_156:
	v_cmp_eq_u32_e32 vcc, s33, v248
	s_cbranch_vccnz rsc_hit_3
	s_lshl_b32 s2, s33, 8
	s_add_i32 s2, s2, s48
	v_or_b32_e32 v144, s2, v146
	v_ashrrev_i32_e32 v145, 31, v144
	v_lshl_add_u64 v[154:155], v[144:145], 2, s[72:73]
	global_load_dword v145, v[154:155], off
	global_load_dword v162, v[154:155], off offset:64
	global_load_dword v163, v[154:155], off offset:128
	global_load_dword v164, v[154:155], off offset:192
	global_load_dword v165, v[154:155], off offset:512
	global_load_dword v166, v[154:155], off offset:576
	global_load_dword v167, v[154:155], off offset:640
	global_load_dword v168, v[154:155], off offset:704
	v_lshl_or_b32 v154, s57, 7, v148
	v_pk_mul_f32 v[156:157], v[108:109], v[120:121]
	s_ashr_i32 s3, s2, 13
	v_pk_mul_f32 v[158:159], v[106:107], v[114:115]
	v_ashrrev_i32_e32 v155, 31, v154
	v_bitop3_b32 v114, s2, v153, v146 bitop3:0xc8
	s_mul_hi_i32 s19, s3, 0x4400000
	s_mul_i32 s3, s3, 0x4400000
	v_readlane_b32 s24, v235, 44
	v_pk_mul_f32 v[160:161], v[104:105], v[112:113]
	v_lshlrev_b64 v[112:113], 1, v[154:155]
	v_mul_u32_u24_e32 v114, 0xb40, v114
	v_readlane_b32 s25, v235, 45
	s_add_u32 s2, s24, s3
	v_lshlrev_b32_e32 v138, 1, v114
	s_addc_u32 s3, s25, s19
	v_lshl_add_u64 v[114:115], s[2:3], 0, v[138:139]
	v_pk_mul_f32 v[124:125], v[116:117], v[124:125]
	v_pk_mul_f32 v[126:127], v[118:119], v[126:127]
	v_pk_mul_f32 v[122:123], v[110:111], v[122:123]
	v_lshl_add_u64 v[114:115], v[114:115], 0, v[112:113]
	v_pk_mul_f32 v[96:97], v[100:101], v[96:97]
	v_pk_mul_f32 v[98:99], v[102:103], v[98:99]
	v_pk_mul_f32 v[88:89], v[92:93], v[88:89]
	v_pk_mul_f32 v[90:91], v[94:95], v[90:91]
	v_pk_mul_f32 v[80:81], v[84:85], v[80:81]
	v_pk_mul_f32 v[82:83], v[86:87], v[82:83]
	v_pk_mul_f32 v[72:73], v[76:77], v[72:73]
	v_pk_mul_f32 v[74:75], v[78:79], v[74:75]
	v_pk_mul_f32 v[64:65], v[68:69], v[64:65]
	v_pk_mul_f32 v[66:67], v[70:71], v[66:67]
	s_mov_b32 s2, 0x43000
	v_pk_mul_f32 v[56:57], v[60:61], v[56:57]
	v_pk_mul_f32 v[58:59], v[62:63], v[58:59]
	v_pk_mul_f32 v[48:49], v[52:53], v[48:49]
	v_pk_mul_f32 v[50:51], v[54:55], v[50:51]
	v_pk_mul_f32 v[40:41], v[44:45], v[40:41]
	v_pk_mul_f32 v[42:43], v[46:47], v[42:43]
	v_pk_mul_f32 v[32:33], v[36:37], v[32:33]
	v_pk_mul_f32 v[34:35], v[38:39], v[34:35]
	v_pk_mul_f32 v[24:25], v[28:29], v[24:25]
	v_pk_mul_f32 v[26:27], v[30:31], v[26:27]
	v_pk_mul_f32 v[16:17], v[20:21], v[16:17]
	v_pk_mul_f32 v[18:19], v[22:23], v[18:19]
	v_pk_mul_f32 v[8:9], v[12:13], v[8:9]
	v_pk_mul_f32 v[10:11], v[14:15], v[10:11]
	v_pk_mul_f32 v[0:1], v[4:5], v[0:1]
	v_pk_mul_f32 v[2:3], v[6:7], v[2:3]
	s_and_b64 vcc, exec, s[16:17]
	s_cbranch_vccz late_align_4
	s_barrier
late_align_4:
	s_waitcnt vmcnt(0)
	v_fmamk_f32 v120, v145, 0x3a800000, v152
	v_fmamk_f32 v121, v162, 0x3a800000, v152
	v_fmamk_f32 v138, v163, 0x3a800000, v152
	v_fmamk_f32 v145, v164, 0x3a800000, v152
	v_rsq_f32_e32 v164, v120
	s_nop 0
	v_mov_b32_e32 v240, v164
	v_fmamk_f32 v154, v165, 0x3a800000, v152
	v_rsq_f32_e32 v165, v121
	s_nop 0
	v_mov_b32_e32 v241, v165
	v_fmamk_f32 v162, v167, 0x3a800000, v152
	v_rsq_f32_e32 v170, v138
	s_nop 0
	v_mov_b32_e32 v242, v170
	v_mul_f32_e32 v138, 0xbfb8aa3b, v164
	v_fmamk_f32 v163, v168, 0x3a800000, v152
	v_rsq_f32_e32 v121, v162
	s_nop 0
	v_mov_b32_e32 v246, v121
	v_mul_f32_e32 v162, 0xbfb8aa3b, v165
	v_pk_mul_f32 v[116:117], v[116:117], v[138:139] op_sel_hi:[1,0]
	v_pk_mul_f32 v[108:109], v[108:109], v[138:139] op_sel_hi:[1,0]
	v_pk_mul_f32 v[118:119], v[118:119], v[138:139] op_sel_hi:[1,0]
	v_pk_mul_f32 v[110:111], v[110:111], v[138:139] op_sel_hi:[1,0]
	v_pk_mul_f32 v[104:105], v[104:105], v[162:163] op_sel_hi:[1,0]
	v_exp_f32_e32 v116, v116
	v_exp_f32_e32 v117, v117
	v_exp_f32_e32 v108, v108
	v_exp_f32_e32 v109, v109
	v_pk_mul_f32 v[106:107], v[106:107], v[162:163] op_sel_hi:[1,0]
	v_exp_f32_e32 v118, v118
	v_exp_f32_e32 v119, v119
	v_exp_f32_e32 v110, v110
	v_exp_f32_e32 v111, v111
	v_exp_f32_e32 v104, v104
	v_exp_f32_e32 v105, v105
	v_exp_f32_e32 v106, v106
	v_exp_f32_e32 v107, v107
	v_fmamk_f32 v155, v166, 0x3a800000, v152
	v_pk_add_f32 v[116:117], v[116:117], 1.0 op_sel_hi:[1,0]
	v_pk_add_f32 v[108:109], v[108:109], 1.0 op_sel_hi:[1,0]
	v_rsq_f32_e32 v155, v155
	s_nop 0
	v_mov_b32_e32 v245, v155
	v_pk_add_f32 v[118:119], v[118:119], 1.0 op_sel_hi:[1,0]
	v_pk_add_f32 v[110:111], v[110:111], 1.0 op_sel_hi:[1,0]
	v_pk_add_f32 v[104:105], v[104:105], 1.0 op_sel_hi:[1,0]
	v_rcp_f32_e32 v116, v116
	v_rcp_f32_e32 v117, v117
	v_rcp_f32_e32 v108, v108
	v_rcp_f32_e32 v109, v109
	v_pk_add_f32 v[106:107], v[106:107], 1.0 op_sel_hi:[1,0]
	v_rcp_f32_e32 v118, v118
	v_rcp_f32_e32 v119, v119
	v_rcp_f32_e32 v110, v110
	v_rcp_f32_e32 v111, v111
	v_rcp_f32_e32 v104, v104
	v_rcp_f32_e32 v105, v105
	v_rcp_f32_e32 v168, v106
	v_rcp_f32_e32 v169, v107
	v_rsq_f32_e32 v171, v154
	s_nop 0
	v_mov_b32_e32 v244, v171
	v_mul_f32_e32 v154, v164, v164
	v_mul_f32_e32 v164, v165, v165
	v_pk_mul_f32 v[106:107], v[154:155], v[116:117] op_sel_hi:[0,1]
	v_pk_mul_f32 v[108:109], v[154:155], v[108:109] op_sel_hi:[0,1]
	v_pk_mul_f32 v[116:117], v[154:155], v[118:119] op_sel_hi:[0,1]
	v_pk_mul_f32 v[110:111], v[154:155], v[110:111] op_sel_hi:[0,1]
	v_pk_mul_f32 v[104:105], v[164:165], v[104:105] op_sel_hi:[0,1]
	v_pk_mul_f32 v[106:107], v[124:125], v[106:107]
	v_pk_mul_f32 v[108:109], v[156:157], v[108:109]
	v_pk_mul_f32 v[166:167], v[100:101], v[162:163] op_sel_hi:[1,0]
	v_pk_mul_f32 v[116:117], v[126:127], v[116:117]
	v_pk_mul_f32 v[110:111], v[122:123], v[110:111]
	v_pk_mul_f32 v[118:119], v[160:161], v[104:105]
	v_cvt_pk_bf16_f32 v104, v106, v107
	v_cvt_pk_bf16_f32 v105, v116, v117
	v_cvt_pk_bf16_f32 v106, v108, v109
	v_cvt_pk_bf16_f32 v107, v110, v111
	v_pk_mul_f32 v[108:109], v[164:165], v[168:169] op_sel_hi:[0,1]
	global_store_dwordx4 v[114:115], v[104:107], off
	v_pk_mul_f32 v[108:109], v[158:159], v[108:109]
	v_rsq_f32_e32 v145, v145
	s_nop 0
	v_mov_b32_e32 v243, v145
	v_exp_f32_e32 v106, v166
	v_exp_f32_e32 v107, v167
	v_cvt_pk_bf16_f32 v104, v118, v119
	v_cvt_pk_bf16_f32 v105, v108, v109
	v_pk_mul_f32 v[108:109], v[102:103], v[162:163] op_sel_hi:[1,0]
	v_pk_add_f32 v[106:107], v[106:107], 1.0 op_sel_hi:[1,0]
	v_exp_f32_e32 v108, v108
	v_exp_f32_e32 v109, v109
	v_rcp_f32_e32 v106, v106
	v_rcp_f32_e32 v107, v107
	v_rsq_f32_e32 v120, v163
	s_nop 0
	v_mov_b32_e32 v247, v120
	v_mov_b32_e32 v248, s33
	s_branch rsc_join_3
; __device__ __forceinline__ unsigned cvt_pk_bf16(float lo, float hi) { unsigned r; asm volatile("v_cvt_pk_bf16_f32 %0, %1, %2" : "=v"(r) : "v"(lo), "v"(hi)); return r; }
;     __device__ __forceinline__ void operator()(const f32x4 (&acc)[2][2][4][2], const Unit& u, int wr, int wc, int fr, int fq) const {
;         const int row0 = u.pm * BM + wr * 64 + fr, col0 = u.pn * HALF + wc * 32 + 8 * fq;
;         float rs[2][4]; load_rs<NP>(ssp, row0, fq, rs);
; #pragma unroll
;         for (int ai = 0; ai < 2; ++ai)
; #pragma unroll
;             for (int m = 0; m < 4; ++m) {
;                 const int row = row0 + ai * HALF + m * 16; const float r = rs[ai][m];
;                 const float nrl = r * -1.44269504089f, r2 = r * r;
;                 unsigned pk[4];
; #pragma unroll
;                 for (int q = 0; q < 4; ++q) {
;                     const f32x4 ga = acc[ai][0][m][q >> 1], ua = acc[ai][1][m][q >> 1]; const int e0 = 2 * (q & 1);
;                     const f32x2 g = (f32x2){ga[e0], ga[e0 + 1]}, up = (f32x2){ua[e0], ua[e0 + 1]};
;                     const f32x2 t = g * nrl; f32x2 ex; ex.x = __builtin_amdgcn_exp2f(t.x); ex.y = __builtin_amdgcn_exp2f(t.y);
;                     const f32x2 d = ex + 1.0f; f32x2 rc; rc.x = __builtin_amdgcn_rcpf(d.x); rc.y = __builtin_amdgcn_rcpf(d.y);
;                     const f32x2 o = (g * up) * (rc * r2);
;                     pk[q] = cvt_pk_bf16(o.x, o.y);
;                 }
;                 u32x4 w; w.x = pk[0]; w.y = pk[1]; w.z = pk[2]; w.w = pk[3];
;                 *(u32x4*)(U + (size_t)(row >> 13) * U_SLAB + (size_t)(row & (SEQ - 1)) * U_PITCH + col0) = w;
rsc_hit_3:
	s_lshl_b32 s2, s33, 8
	s_add_i32 s2, s2, s48
	v_or_b32_e32 v144, s2, v146
	v_lshl_or_b32 v154, s57, 7, v148
	v_pk_mul_f32 v[156:157], v[108:109], v[120:121]
	s_ashr_i32 s3, s2, 13
	v_pk_mul_f32 v[158:159], v[106:107], v[114:115]
	v_ashrrev_i32_e32 v155, 31, v154
	v_bitop3_b32 v114, s2, v153, v146 bitop3:0xc8
	s_mul_hi_i32 s19, s3, 0x4400000
	s_mul_i32 s3, s3, 0x4400000
	v_readlane_b32 s24, v235, 44
	v_pk_mul_f32 v[160:161], v[104:105], v[112:113]
	v_lshlrev_b64 v[112:113], 1, v[154:155]
	v_mul_u32_u24_e32 v114, 0xb40, v114
	v_readlane_b32 s25, v235, 45
	s_add_u32 s2, s24, s3
	v_lshlrev_b32_e32 v138, 1, v114
	s_addc_u32 s3, s25, s19
	v_lshl_add_u64 v[114:115], s[2:3], 0, v[138:139]
	v_pk_mul_f32 v[124:125], v[116:117], v[124:125]
	v_pk_mul_f32 v[126:127], v[118:119], v[126:127]
	v_pk_mul_f32 v[122:123], v[110:111], v[122:123]
	v_lshl_add_u64 v[114:115], v[114:115], 0, v[112:113]
	v_pk_mul_f32 v[96:97], v[100:101], v[96:97]
	v_pk_mul_f32 v[98:99], v[102:103], v[98:99]
	v_pk_mul_f32 v[88:89], v[92:93], v[88:89]
	v_pk_mul_f32 v[90:91], v[94:95], v[90:91]
	v_pk_mul_f32 v[80:81], v[84:85], v[80:81]
	v_pk_mul_f32 v[82:83], v[86:87], v[82:83]
	v_pk_mul_f32 v[72:73], v[76:77], v[72:73]
	v_pk_mul_f32 v[74:75], v[78:79], v[74:75]
	v_pk_mul_f32 v[64:65], v[68:69], v[64:65]
	v_pk_mul_f32 v[66:67], v[70:71], v[66:67]
	s_mov_b32 s2, 0x43000
	v_pk_mul_f32 v[56:57], v[60:61], v[56:57]
	v_pk_mul_f32 v[58:59], v[62:63], v[58:59]
	v_pk_mul_f32 v[48:49], v[52:53], v[48:49]
	v_pk_mul_f32 v[50:51], v[54:55], v[50:51]
	v_pk_mul_f32 v[40:41], v[44:45], v[40:41]
	v_pk_mul_f32 v[42:43], v[46:47], v[42:43]
	v_pk_mul_f32 v[32:33], v[36:37], v[32:33]
	v_pk_mul_f32 v[34:35], v[38:39], v[34:35]
	v_pk_mul_f32 v[24:25], v[28:29], v[24:25]
	v_pk_mul_f32 v[26:27], v[30:31], v[26:27]
	v_pk_mul_f32 v[16:17], v[20:21], v[16:17]
	v_pk_mul_f32 v[18:19], v[22:23], v[18:19]
	v_pk_mul_f32 v[8:9], v[12:13], v[8:9]
	v_pk_mul_f32 v[10:11], v[14:15], v[10:11]
	v_pk_mul_f32 v[0:1], v[4:5], v[0:1]
	v_pk_mul_f32 v[2:3], v[6:7], v[2:3]
	v_mov_b32_e32 v164, v240
	s_nop 0
	v_mov_b32_e32 v165, v241
	s_nop 0
	v_mov_b32_e32 v170, v242
	v_mul_f32_e32 v138, 0xbfb8aa3b, v164
	s_nop 0
	v_mov_b32_e32 v121, v246
	v_mul_f32_e32 v162, 0xbfb8aa3b, v165
	v_pk_mul_f32 v[116:117], v[116:117], v[138:139] op_sel_hi:[1,0]
	v_pk_mul_f32 v[108:109], v[108:109], v[138:139] op_sel_hi:[1,0]
	v_pk_mul_f32 v[118:119], v[118:119], v[138:139] op_sel_hi:[1,0]
	v_pk_mul_f32 v[110:111], v[110:111], v[138:139] op_sel_hi:[1,0]
	v_pk_mul_f32 v[104:105], v[104:105], v[162:163] op_sel_hi:[1,0]
	v_exp_f32_e32 v116, v116
	v_exp_f32_e32 v117, v117
	v_exp_f32_e32 v108, v108
	v_exp_f32_e32 v109, v109
	v_pk_mul_f32 v[106:107], v[106:107], v[162:163] op_sel_hi:[1,0]
	v_exp_f32_e32 v118, v118
	v_exp_f32_e32 v119, v119
	v_exp_f32_e32 v110, v110
	v_exp_f32_e32 v111, v111
	v_exp_f32_e32 v104, v104
	v_exp_f32_e32 v105, v105
	v_exp_f32_e32 v106, v106
	v_exp_f32_e32 v107, v107
	s_nop 0
	v_pk_add_f32 v[116:117], v[116:117], 1.0 op_sel_hi:[1,0]
	v_pk_add_f32 v[108:109], v[108:109], 1.0 op_sel_hi:[1,0]
	v_mov_b32_e32 v155, v245
	v_pk_add_f32 v[118:119], v[118:119], 1.0 op_sel_hi:[1,0]
	v_pk_add_f32 v[110:111], v[110:111], 1.0 op_sel_hi:[1,0]
	v_pk_add_f32 v[104:105], v[104:105], 1.0 op_sel_hi:[1,0]
	v_rcp_f32_e32 v116, v116
	v_rcp_f32_e32 v117, v117
	v_rcp_f32_e32 v108, v108
	v_rcp_f32_e32 v109, v109
	v_pk_add_f32 v[106:107], v[106:107], 1.0 op_sel_hi:[1,0]
	v_rcp_f32_e32 v118, v118
	v_rcp_f32_e32 v119, v119
	v_rcp_f32_e32 v110, v110
	v_rcp_f32_e32 v111, v111
	v_rcp_f32_e32 v104, v104
	v_rcp_f32_e32 v105, v105
	v_rcp_f32_e32 v168, v106
	v_rcp_f32_e32 v169, v107
	v_mov_b32_e32 v171, v244
	v_mul_f32_e32 v154, v164, v164
	v_mul_f32_e32 v164, v165, v165
	v_pk_mul_f32 v[106:107], v[154:155], v[116:117] op_sel_hi:[0,1]
	v_pk_mul_f32 v[108:109], v[154:155], v[108:109] op_sel_hi:[0,1]
	v_pk_mul_f32 v[116:117], v[154:155], v[118:119] op_sel_hi:[0,1]
	v_pk_mul_f32 v[110:111], v[154:155], v[110:111] op_sel_hi:[0,1]
	v_pk_mul_f32 v[104:105], v[164:165], v[104:105] op_sel_hi:[0,1]
	v_pk_mul_f32 v[106:107], v[124:125], v[106:107]
	v_pk_mul_f32 v[108:109], v[156:157], v[108:109]
	v_pk_mul_f32 v[166:167], v[100:101], v[162:163] op_sel_hi:[1,0]
	v_pk_mul_f32 v[116:117], v[126:127], v[116:117]
	v_pk_mul_f32 v[110:111], v[122:123], v[110:111]
	v_pk_mul_f32 v[118:119], v[160:161], v[104:105]
	v_cvt_pk_bf16_f32 v104, v106, v107
	v_cvt_pk_bf16_f32 v105, v116, v117
	v_cvt_pk_bf16_f32 v106, v108, v109
	v_cvt_pk_bf16_f32 v107, v110, v111
	v_pk_mul_f32 v[108:109], v[164:165], v[168:169] op_sel_hi:[0,1]
	global_store_dwordx4 v[114:115], v[104:107], off
	s_and_b64 vcc, exec, s[16:17]
	s_cbranch_vccz late_align_5
	s_barrier
late_align_5:
	v_pk_mul_f32 v[108:109], v[158:159], v[108:109]
	v_mov_b32_e32 v145, v243
	v_exp_f32_e32 v106, v166
	v_exp_f32_e32 v107, v167
	v_cvt_pk_bf16_f32 v104, v118, v119
	v_cvt_pk_bf16_f32 v105, v108, v109
	v_pk_mul_f32 v[108:109], v[102:103], v[162:163] op_sel_hi:[1,0]
	v_pk_add_f32 v[106:107], v[106:107], 1.0 op_sel_hi:[1,0]
	v_exp_f32_e32 v108, v108
	v_exp_f32_e32 v109, v109
	v_rcp_f32_e32 v106, v106
	v_rcp_f32_e32 v107, v107
	v_mov_b32_e32 v120, v247
	s_waitcnt lgkmcnt(0)

; template <int NP> __device__ __forceinline__ void load_rs(const float* ssp, int row0, int fq, float (&rs)[2][4]) {
;     ...
;     } else {
;         f32x4 p[2][4];
; #pragma unroll
;         for (int ai = 0; ai < 2; ++ai)
; #pragma unroll
;             for (int m = 0; m < 4; ++m) p[ai][m] = *(const f32x4*)(ssp + (size_t)(row0 + ai * HALF + m * 16) * 16 + 4 * fq);
; #pragma unroll
;         for (int ai = 0; ai < 2; ++ai)
; #pragma unroll
;             for (int m = 0; m < 4; ++m) { float s = (p[ai][m][0] + p[ai][m][1]) + (p[ai][m][2] + p[ai][m][3]); s += __shfl_xor(s, 16); s += __shfl_xor(s, 32); rs[ai][m] = s; }
;     }
; #pragma unroll
;     for (int ai = 0; ai < 2; ++ai)
; #pragma unroll
;         for (int m = 0; m < 4; ++m) rs[ai][m] = __builtin_amdgcn_rsqf(rs[ai][m] * (1.0f / D_MODEL) + RMS_EPS);
;     template <bool GATE> __device__ __forceinline__ void body(const f32x4 (&acc)[2][2][4][2], const Unit& u, int wr, int wc, int fr, int fq) const {
;         const int row0 = u.pm * BM + wr * 64 + fr, col0 = u.pn * BM + wc * 32 + 8 * fq;
;         float rs[2][4]; load_rs<16>(ssp, row0, fq, rs);
; #pragma unroll
;         for (int ai = 0; ai < 2; ++ai)
; #pragma unroll
;             for (int m = 0; m < 4; ++m) {
;                 const int row = row0 + ai * HALF + m * 16; const float r = rs[ai][m], nrl = r * -1.44269504089f;
.LBB0_382:
	v_cmp_eq_u32_e32 vcc, s33, v248
	s_cbranch_vccnz rsc_hit_2
	v_lshl_add_u32 v186, s33, 8, v193
	v_or_b32_e32 v184, 16, v186
	v_ashrrev_i32_e32 v187, 31, v186
	v_ashrrev_i32_e32 v185, 31, v184
	v_lshlrev_b64 v[128:129], 6, v[186:187]
	v_lshlrev_b64 v[130:131], 6, v[184:185]
	v_or_b32_e32 v182, 32, v186
	v_or_b32_e32 v180, 48, v186
	v_lshl_add_u64 v[128:129], v[162:163], 0, v[128:129]
	v_lshl_add_u64 v[130:131], v[162:163], 0, v[130:131]
	v_ashrrev_i32_e32 v183, 31, v182
	v_ashrrev_i32_e32 v181, 31, v180
	global_load_dwordx4 v[148:151], v[128:129], off
	global_load_dwordx4 v[204:207], v[130:131], off
	v_lshlrev_b64 v[128:129], 6, v[182:183]
	v_lshlrev_b64 v[130:131], 6, v[180:181]
	v_add_u32_e32 v178, 0x80, v186
	v_add_u32_e32 v176, 0x90, v186
	v_lshl_add_u64 v[128:129], v[162:163], 0, v[128:129]
	v_lshl_add_u64 v[130:131], v[162:163], 0, v[130:131]
	v_ashrrev_i32_e32 v179, 31, v178
	v_ashrrev_i32_e32 v177, 31, v176
	global_load_dwordx4 v[208:211], v[128:129], off
	global_load_dwordx4 v[140:143], v[130:131], off
	v_lshlrev_b64 v[128:129], 6, v[178:179]
	v_lshlrev_b64 v[130:131], 6, v[176:177]
	v_add_u32_e32 v174, 0xa0, v186
	v_add_u32_e32 v170, 0xb0, v186
	v_lshl_add_u64 v[128:129], v[162:163], 0, v[128:129]
	v_lshl_add_u64 v[130:131], v[162:163], 0, v[130:131]
	v_ashrrev_i32_e32 v175, 31, v174
	v_ashrrev_i32_e32 v171, 31, v170
	global_load_dwordx4 v[144:147], v[128:129], off
	global_load_dwordx4 v[132:135], v[130:131], off
	v_lshlrev_b64 v[128:129], 6, v[174:175]
	v_lshlrev_b64 v[130:131], 6, v[170:171]
	v_lshl_add_u64 v[128:129], v[162:163], 0, v[128:129]
	v_lshl_add_u64 v[130:131], v[162:163], 0, v[130:131]
	global_load_dwordx4 v[136:139], v[128:129], off
	s_nop 0
	global_load_dwordx4 v[128:131], v[130:131], off
	v_and_b32_e32 v172, 64, v201
	v_xor_b32_e32 v171, 16, v201
	v_add_u32_e32 v172, 64, v172
	v_xor_b32_e32 v173, 32, v201
	s_and_b64 vcc, exec, s[8:9]
	s_cbranch_vccz late_align_6
	s_barrier
; template <int NP> __device__ __forceinline__ void load_rs(const float* ssp, int row0, int fq, float (&rs)[2][4]) {
;     ...
;     } else {
;         f32x4 p[2][4];
; #pragma unroll
;         for (int ai = 0; ai < 2; ++ai)
; #pragma unroll
;             for (int m = 0; m < 4; ++m) p[ai][m] = *(const f32x4*)(ssp + (size_t)(row0 + ai * HALF + m * 16) * 16 + 4 * fq);
; #pragma unroll
;         for (int ai = 0; ai < 2; ++ai)
; #pragma unroll
;             for (int m = 0; m < 4; ++m) { float s = (p[ai][m][0] + p[ai][m][1]) + (p[ai][m][2] + p[ai][m][3]); s += __shfl_xor(s, 16); s += __shfl_xor(s, 32); rs[ai][m] = s; }
;     }
; #pragma unroll
;     for (int ai = 0; ai < 2; ++ai)
; #pragma unroll
;         for (int m = 0; m < 4; ++m) rs[ai][m] = __builtin_amdgcn_rsqf(rs[ai][m] * (1.0f / D_MODEL) + RMS_EPS);
;     __device__ __forceinline__ void operator()(const f32x4 (&acc)[2][2][4][2], const Unit& u, int wr, int wc, int fr, int fq) const {
;         if (u.pn >= 9) body<true>(acc, u, wr, wc, fr, fq); else body<false>(acc, u, wr, wc, fr, fq);
late_align_6:
	v_cmp_lt_i32_e32 vcc, v171, v172
	s_cmp_lt_i32 s43, 9
	v_lshl_or_b32 v160, s43, 8, v197
	v_cndmask_b32_e32 v171, v201, v171, vcc
	v_cmp_lt_i32_e32 vcc, v173, v172
	v_lshlrev_b32_e32 v175, 2, v171
	s_waitcnt vmcnt(0)
	v_add_f32_e32 v148, v148, v149
	v_add_f32_e32 v149, v150, v151
	v_cndmask_b32_e32 v172, v201, v173, vcc
	v_add_f32_e32 v177, v148, v149
	v_add_f32_e32 v148, v204, v205
	v_add_f32_e32 v149, v206, v207
	v_lshlrev_b32_e32 v171, 2, v172
	v_add_f32_e32 v179, v148, v149
	v_add_f32_e32 v150, v208, v209
	v_add_f32_e32 v151, v210, v211
	v_add_f32_e32 v181, v150, v151
	s_cbranch_scc0 .LBB0_384
	v_mov_b32_e32 v236, v177
	v_mov_b32_e32 v237, v177
	s_nop 1
	v_permlane16_swap_b32_e32 v236, v237
	v_cndmask_b32_e64 v150, v237, v236, s[98:99]
	v_mov_b32_e32 v236, v179
	v_mov_b32_e32 v237, v179
	s_nop 1
	v_permlane16_swap_b32_e32 v236, v237
	v_cndmask_b32_e64 v151, v237, v236, s[98:99]
	v_mov_b32_e32 v148, v141
	v_mov_b32_e32 v149, v142
	v_mov_b32_e32 v236, v181
	v_mov_b32_e32 v237, v181
	s_nop 1
	v_permlane16_swap_b32_e32 v236, v237
	v_cndmask_b32_e64 v172, v237, v236, s[98:99]
	s_waitcnt lgkmcnt(2)
	v_add_f32_e32 v150, v177, v150
	v_mov_b32_e32 v236, v150
	v_mov_b32_e32 v237, v150
	s_nop 1
	v_permlane32_swap_b32_e32 v236, v237
	v_cndmask_b32_e64 v173, v237, v236, s[100:101]
	s_waitcnt lgkmcnt(2)
	v_add_f32_e32 v183, v179, v151
	v_mov_b32_e32 v151, v143
	v_mov_b32_e32 v236, v183
	v_mov_b32_e32 v237, v183
	s_nop 1
	v_permlane32_swap_b32_e32 v236, v237
	v_cndmask_b32_e64 v185, v237, v236, s[100:101]
	s_waitcnt lgkmcnt(2)
	v_add_f32_e32 v172, v181, v172
	s_waitcnt lgkmcnt(1)
	v_add_f32_e32 v173, v150, v173
	v_mov_b32_e32 v150, v140
	v_pk_add_f32 v[148:149], v[148:149], v[150:151]
	v_mov_b32_e32 v150, v144
	v_add_f32_e32 v188, v148, v149
	v_mov_b32_e32 v148, v145
	v_mov_b32_e32 v149, v146
	v_mov_b32_e32 v151, v147
	v_pk_add_f32 v[148:149], v[148:149], v[150:151]
	v_mov_b32_e32 v236, v188
	v_mov_b32_e32 v237, v188
	s_nop 1
	v_permlane16_swap_b32_e32 v236, v237
	v_cndmask_b32_e64 v190, v237, v236, s[98:99]
	v_add_f32_e32 v148, v148, v149
	v_mov_b32_e32 v236, v148
	v_mov_b32_e32 v237, v148
	s_nop 1
	v_permlane16_swap_b32_e32 v236, v237
	v_cndmask_b32_e64 v149, v237, v236, s[98:99]
	s_waitcnt lgkmcnt(2)
	v_add_f32_e32 v183, v183, v185
	v_mov_b32_e32 v150, v132
	s_waitcnt lgkmcnt(1)
	v_add_f32_e32 v185, v188, v190
	v_mov_b32_e32 v151, v135
	s_waitcnt lgkmcnt(0)
	v_add_f32_e32 v188, v148, v149
	v_mov_b32_e32 v148, v133
	v_mov_b32_e32 v149, v134
	v_pk_add_f32 v[148:149], v[148:149], v[150:151]
	v_mov_b32_e32 v150, v136
	v_add_f32_e32 v191, v148, v149
	v_mov_b32_e32 v148, v137
	v_mov_b32_e32 v149, v138
	v_mov_b32_e32 v151, v139
	v_pk_add_f32 v[148:149], v[148:149], v[150:151]
	v_mov_b32_e32 v150, v128
	v_add_f32_e32 v194, v148, v149
	v_mov_b32_e32 v148, v129
	v_mov_b32_e32 v149, v130
	v_mov_b32_e32 v151, v131
	v_pk_add_f32 v[148:149], v[148:149], v[150:151]
	v_mov_b32_e32 v236, v172
	v_mov_b32_e32 v237, v172
	s_nop 1
	v_permlane32_swap_b32_e32 v236, v237
	v_cndmask_b32_e64 v187, v237, v236, s[100:101]
	v_add_f32_e32 v148, v148, v149
	v_mov_b32_e32 v236, v148
	v_mov_b32_e32 v237, v148
	s_nop 1
	v_permlane16_swap_b32_e32 v236, v237
	v_cndmask_b32_e64 v149, v237, v236, s[98:99]
	v_mov_b32_e32 v236, v191
	v_mov_b32_e32 v237, v191
	s_nop 1
	v_permlane16_swap_b32_e32 v236, v237
	v_cndmask_b32_e64 v192, v237, v236, s[98:99]
	v_mov_b32_e32 v236, v194
	v_mov_b32_e32 v237, v194
	s_nop 1
	v_permlane16_swap_b32_e32 v236, v237
	v_cndmask_b32_e64 v203, v237, v236, s[98:99]
	s_waitcnt lgkmcnt(3)
	v_add_f32_e32 v172, v172, v187
	v_mov_b32_e32 v236, v185
	v_mov_b32_e32 v237, v185
	s_nop 1
	v_permlane32_swap_b32_e32 v236, v237
	v_cndmask_b32_e64 v187, v237, v236, s[100:101]
	s_waitcnt lgkmcnt(3)
	v_add_f32_e32 v148, v148, v149
	v_mov_b32_e32 v236, v148
	v_mov_b32_e32 v237, v148
	s_nop 1
	v_permlane32_swap_b32_e32 v236, v237
	v_cndmask_b32_e64 v149, v237, v236, s[100:101]
	v_mov_b32_e32 v236, v188
	v_mov_b32_e32 v237, v188
	s_nop 1
	v_permlane32_swap_b32_e32 v236, v237
	v_cndmask_b32_e64 v190, v237, v236, s[100:101]
	s_waitcnt lgkmcnt(4)
	v_add_f32_e32 v150, v191, v192
	v_mov_b32_e32 v236, v150
	v_mov_b32_e32 v237, v150
	s_nop 1
	v_permlane32_swap_b32_e32 v236, v237
	v_cndmask_b32_e64 v151, v237, v236, s[100:101]
	s_waitcnt lgkmcnt(4)
	v_add_f32_e32 v191, v194, v203
	v_mov_b32_e32 v236, v191
	v_mov_b32_e32 v237, v191
	s_nop 1
	v_permlane32_swap_b32_e32 v236, v237
	v_cndmask_b32_e64 v192, v237, v236, s[100:101]
	s_waitcnt lgkmcnt(3)
	v_add_f32_e32 v148, v148, v149
	v_fmamk_f32 v149, v173, 0x3a800000, v202
	v_rsq_f32_e32 v208, v149
	s_nop 0
	v_mov_b32_e32 v240, v208
	v_fmamk_f32 v149, v183, 0x3a800000, v202
	v_add_f32_e32 v185, v185, v187
	v_rsq_f32_e32 v210, v149
	s_nop 0
	v_mov_b32_e32 v241, v210
	v_fmamk_f32 v149, v172, 0x3a800000, v202
	s_waitcnt lgkmcnt(2)
	v_add_f32_e32 v187, v188, v190
	v_rsq_f32_e32 v212, v149
	s_nop 0
	v_mov_b32_e32 v242, v212
	v_fmamk_f32 v149, v185, 0x3a800000, v202
	s_waitcnt lgkmcnt(1)
	v_add_f32_e32 v150, v150, v151
	v_rsq_f32_e32 v214, v149
	s_nop 0
	v_mov_b32_e32 v243, v214
	v_fmamk_f32 v149, v187, 0x3a800000, v202
	s_waitcnt lgkmcnt(0)
	v_add_f32_e32 v151, v191, v192
	v_rsq_f32_e32 v194, v149
	s_nop 0
	v_mov_b32_e32 v244, v194
	v_fmamk_f32 v149, v150, 0x3a800000, v202
	v_rsq_f32_e32 v192, v149
	s_nop 0
	v_mov_b32_e32 v245, v192
	v_fmamk_f32 v149, v151, 0x3a800000, v202
	v_fmamk_f32 v148, v148, 0x3a800000, v202
	v_rsq_f32_e32 v190, v149
	s_nop 0
	v_mov_b32_e32 v246, v190
	v_rsq_f32_e32 v188, v148
	s_nop 0
	v_mov_b32_e32 v247, v188
	v_mov_b32_e32 v248, s33

; __device__ __forceinline__ unsigned cvt_pk_bf16(float lo, float hi) { unsigned r; asm volatile("v_cvt_pk_bf16_f32 %0, %1, %2" : "=v"(r) : "v"(lo), "v"(hi)); return r; }
;     template <bool GATE> __device__ __forceinline__ void body(const f32x4 (&acc)[2][2][4][2], const Unit& u, int wr, int wc, int fr, int fq) const {
;     ...
;             for (int m = 0; m < 4; ++m) {
;                 const int row = row0 + ai * HALF + m * 16; const float r = rs[ai][m], nrl = r * -1.44269504089f;
; #pragma unroll
;                 for (int bj = 0; bj < 2; ++bj) {
;                     unsigned pk[4];
; #pragma unroll
;                     for (int q = 0; q < 4; ++q) {
;                         const f32x4 va = acc[ai][bj][m][q >> 1]; const int e0 = 2 * (q & 1);
;                         const f32x2 v = (f32x2){va[e0], va[e0 + 1]};
;                         f32x2 o;
;                         if (GATE) { const f32x2 t = v * nrl; f32x2 ex; ex.x = __builtin_amdgcn_exp2f(t.x); ex.y = __builtin_amdgcn_exp2f(t.y);
;                             const f32x2 d = ex + 1.0f; o.x = __builtin_amdgcn_rcpf(d.x); o.y = __builtin_amdgcn_rcpf(d.y); }
;                         else o = v * r;
;                         pk[q] = cvt_pk_bf16(o.x, o.y);
;                     }
;                     u32x4 w; w.x = pk[0]; w.y = pk[1]; w.z = pk[2]; w.w = pk[3];
;                     *(u32x4*)(P + (size_t)row * PITCH + col0 + bj * HALF) = w;
late_after_7:
	s_nop 1
	v_pk_mul_f32 v[204:205], v[116:117], v[208:209] op_sel_hi:[1,0]
	v_pk_mul_f32 v[206:207], v[118:119], v[208:209] op_sel_hi:[1,0]
	v_cvt_pk_bf16_f32 v204, v204, v205
	s_nop 0
	v_cvt_pk_bf16_f32 v205, v206, v207
	v_pk_mul_f32 v[206:207], v[112:113], v[208:209] op_sel_hi:[1,0]
	v_pk_mul_f32 v[208:209], v[114:115], v[208:209] op_sel_hi:[1,0]
	v_cvt_pk_bf16_f32 v206, v206, v207
	s_nop 0
	v_cvt_pk_bf16_f32 v207, v208, v209
	global_store_dwordx4 v[216:217], v[204:207], off offset:256
	v_pk_mul_f32 v[208:209], v[106:107], v[210:211] op_sel_hi:[1,0]
	s_nop 0
	v_pk_mul_f32 v[204:205], v[108:109], v[210:211] op_sel_hi:[1,0]
	v_pk_mul_f32 v[206:207], v[110:111], v[210:211] op_sel_hi:[1,0]
	v_cvt_pk_bf16_f32 v204, v204, v205
	s_nop 0
	v_cvt_pk_bf16_f32 v205, v206, v207
	v_pk_mul_f32 v[206:207], v[104:105], v[210:211] op_sel_hi:[1,0]
	s_nop 0
	v_cvt_pk_bf16_f32 v206, v206, v207
	v_cvt_pk_bf16_f32 v207, v208, v209
	v_mad_i64_i32 v[208:209], s[2:3], v184, s41, v[148:149]
	v_lshl_add_u64 v[208:209], v[208:209], 0, v[150:151]
	global_store_dwordx4 v[208:209], v[204:207], off
	s_nop 1
	v_pk_mul_f32 v[204:205], v[100:101], v[210:211] op_sel_hi:[1,0]
	v_pk_mul_f32 v[206:207], v[102:103], v[210:211] op_sel_hi:[1,0]
	v_cvt_pk_bf16_f32 v204, v204, v205
	s_nop 0
	v_cvt_pk_bf16_f32 v205, v206, v207
	v_pk_mul_f32 v[206:207], v[96:97], v[210:211] op_sel_hi:[1,0]
	v_pk_mul_f32 v[210:211], v[98:99], v[210:211] op_sel_hi:[1,0]
	v_cvt_pk_bf16_f32 v206, v206, v207
	s_nop 0
	v_cvt_pk_bf16_f32 v207, v210, v211
	global_store_dwordx4 v[208:209], v[204:207], off offset:256
	v_pk_mul_f32 v[208:209], v[90:91], v[212:213] op_sel_hi:[1,0]
	v_pk_mul_f32 v[210:211], v[82:83], v[212:213] op_sel_hi:[1,0]
	v_pk_mul_f32 v[204:205], v[92:93], v[212:213] op_sel_hi:[1,0]
	v_pk_mul_f32 v[206:207], v[94:95], v[212:213] op_sel_hi:[1,0]
	v_cvt_pk_bf16_f32 v204, v204, v205
	s_nop 0
	v_cvt_pk_bf16_f32 v205, v206, v207
	v_pk_mul_f32 v[206:207], v[88:89], v[212:213] op_sel_hi:[1,0]
	s_nop 0
	v_cvt_pk_bf16_f32 v206, v206, v207
	v_cvt_pk_bf16_f32 v207, v208, v209
	v_mad_i64_i32 v[208:209], s[2:3], v182, s41, v[148:149]
	v_lshl_add_u64 v[208:209], v[208:209], 0, v[150:151]
	global_store_dwordx4 v[208:209], v[204:207], off
	s_nop 1
	v_pk_mul_f32 v[204:205], v[84:85], v[212:213] op_sel_hi:[1,0]
	v_pk_mul_f32 v[206:207], v[86:87], v[212:213] op_sel_hi:[1,0]
	v_cvt_pk_bf16_f32 v204, v204, v205
	s_nop 0
	v_cvt_pk_bf16_f32 v205, v206, v207
	v_pk_mul_f32 v[206:207], v[80:81], v[212:213] op_sel_hi:[1,0]
	s_nop 0
	v_cvt_pk_bf16_f32 v206, v206, v207
	v_cvt_pk_bf16_f32 v207, v210, v211
	global_store_dwordx4 v[208:209], v[204:207], off offset:256
	v_pk_mul_f32 v[208:209], v[74:75], v[214:215] op_sel_hi:[1,0]
	v_pk_mul_f32 v[210:211], v[66:67], v[214:215] op_sel_hi:[1,0]
	v_pk_mul_f32 v[204:205], v[76:77], v[214:215] op_sel_hi:[1,0]
	v_pk_mul_f32 v[206:207], v[78:79], v[214:215] op_sel_hi:[1,0]
	v_cvt_pk_bf16_f32 v204, v204, v205
	s_nop 0
	v_cvt_pk_bf16_f32 v205, v206, v207
	v_pk_mul_f32 v[206:207], v[72:73], v[214:215] op_sel_hi:[1,0]
	s_nop 0
	v_cvt_pk_bf16_f32 v206, v206, v207
	v_cvt_pk_bf16_f32 v207, v208, v209
	v_mad_i64_i32 v[208:209], s[2:3], v180, s41, v[148:149]
	v_lshl_add_u64 v[208:209], v[208:209], 0, v[150:151]
	global_store_dwordx4 v[208:209], v[204:207], off
	s_nop 1
	v_pk_mul_f32 v[204:205], v[68:69], v[214:215] op_sel_hi:[1,0]
	v_pk_mul_f32 v[206:207], v[70:71], v[214:215] op_sel_hi:[1,0]
	v_cvt_pk_bf16_f32 v204, v204, v205
	s_nop 0
	v_cvt_pk_bf16_f32 v205, v206, v207
	v_pk_mul_f32 v[206:207], v[64:65], v[214:215] op_sel_hi:[1,0]
	s_nop 0
	v_cvt_pk_bf16_f32 v206, v206, v207
	v_cvt_pk_bf16_f32 v207, v210, v211
	global_store_dwordx4 v[208:209], v[204:207], off offset:256
	v_pk_mul_f32 v[208:209], v[58:59], v[194:195] op_sel_hi:[1,0]
	v_pk_mul_f32 v[210:211], v[50:51], v[194:195] op_sel_hi:[1,0]
	v_pk_mul_f32 v[204:205], v[60:61], v[194:195] op_sel_hi:[1,0]
	v_pk_mul_f32 v[206:207], v[62:63], v[194:195] op_sel_hi:[1,0]
; __device__ __forceinline__ unsigned cvt_pk_bf16(float lo, float hi) { unsigned r; asm volatile("v_cvt_pk_bf16_f32 %0, %1, %2" : "=v"(r) : "v"(lo), "v"(hi)); return r; }
;     template <bool GATE> __device__ __forceinline__ void body(const f32x4 (&acc)[2][2][4][2], const Unit& u, int wr, int wc, int fr, int fq) const {
;     ...
;             for (int m = 0; m < 4; ++m) {
;                 const int row = row0 + ai * HALF + m * 16; const float r = rs[ai][m], nrl = r * -1.44269504089f;
; #pragma unroll
;                 for (int bj = 0; bj < 2; ++bj) {
;                     unsigned pk[4];
; #pragma unroll
;                     for (int q = 0; q < 4; ++q) {
;                         const f32x4 va = acc[ai][bj][m][q >> 1]; const int e0 = 2 * (q & 1);
;                         const f32x2 v = (f32x2){va[e0], va[e0 + 1]};
;                         f32x2 o;
;                         if (GATE) { const f32x2 t = v * nrl; f32x2 ex; ex.x = __builtin_amdgcn_exp2f(t.x); ex.y = __builtin_amdgcn_exp2f(t.y);
;                             const f32x2 d = ex + 1.0f; o.x = __builtin_amdgcn_rcpf(d.x); o.y = __builtin_amdgcn_rcpf(d.y); }
;                         else o = v * r;
;                         pk[q] = cvt_pk_bf16(o.x, o.y);
;                     }
;                     u32x4 w; w.x = pk[0]; w.y = pk[1]; w.z = pk[2]; w.w = pk[3];
;                     *(u32x4*)(P + (size_t)row * PITCH + col0 + bj * HALF) = w;
	v_cvt_pk_bf16_f32 v204, v204, v205
	s_nop 0
	v_cvt_pk_bf16_f32 v205, v206, v207
	v_pk_mul_f32 v[206:207], v[56:57], v[194:195] op_sel_hi:[1,0]
	s_nop 0
	v_cvt_pk_bf16_f32 v206, v206, v207
	v_cvt_pk_bf16_f32 v207, v208, v209
	v_mad_i64_i32 v[208:209], s[2:3], v178, s41, v[148:149]
	v_lshl_add_u64 v[208:209], v[208:209], 0, v[150:151]
	global_store_dwordx4 v[208:209], v[204:207], off
	s_nop 1
	v_pk_mul_f32 v[204:205], v[52:53], v[194:195] op_sel_hi:[1,0]
	v_pk_mul_f32 v[206:207], v[54:55], v[194:195] op_sel_hi:[1,0]
	v_cvt_pk_bf16_f32 v204, v204, v205
	s_nop 0
	v_cvt_pk_bf16_f32 v205, v206, v207
	v_pk_mul_f32 v[206:207], v[48:49], v[194:195] op_sel_hi:[1,0]
	s_nop 0
	v_cvt_pk_bf16_f32 v206, v206, v207
	v_cvt_pk_bf16_f32 v207, v210, v211
	global_store_dwordx4 v[208:209], v[204:207], off offset:256
	v_pk_mul_f32 v[208:209], v[42:43], v[192:193] op_sel_hi:[1,0]
	v_pk_mul_f32 v[210:211], v[34:35], v[192:193] op_sel_hi:[1,0]
	v_pk_mul_f32 v[204:205], v[44:45], v[192:193] op_sel_hi:[1,0]
	v_pk_mul_f32 v[206:207], v[46:47], v[192:193] op_sel_hi:[1,0]
	v_cvt_pk_bf16_f32 v204, v204, v205
	s_nop 0
	v_cvt_pk_bf16_f32 v205, v206, v207
	v_pk_mul_f32 v[206:207], v[40:41], v[192:193] op_sel_hi:[1,0]
	s_nop 0
	v_cvt_pk_bf16_f32 v206, v206, v207
	v_cvt_pk_bf16_f32 v207, v208, v209
	v_mad_i64_i32 v[208:209], s[2:3], v176, s41, v[148:149]
	v_lshl_add_u64 v[208:209], v[208:209], 0, v[150:151]
	global_store_dwordx4 v[208:209], v[204:207], off
	s_nop 1
	v_pk_mul_f32 v[204:205], v[36:37], v[192:193] op_sel_hi:[1,0]
	v_pk_mul_f32 v[206:207], v[38:39], v[192:193] op_sel_hi:[1,0]
	v_cvt_pk_bf16_f32 v204, v204, v205
	s_nop 0
	v_cvt_pk_bf16_f32 v205, v206, v207
	v_pk_mul_f32 v[206:207], v[32:33], v[192:193] op_sel_hi:[1,0]
	s_nop 0
	v_cvt_pk_bf16_f32 v206, v206, v207
	v_cvt_pk_bf16_f32 v207, v210, v211
	global_store_dwordx4 v[208:209], v[204:207], off offset:256
	v_pk_mul_f32 v[208:209], v[26:27], v[190:191] op_sel_hi:[1,0]
	s_nop 0
	v_pk_mul_f32 v[204:205], v[28:29], v[190:191] op_sel_hi:[1,0]
	v_pk_mul_f32 v[206:207], v[30:31], v[190:191] op_sel_hi:[1,0]
	v_cvt_pk_bf16_f32 v204, v204, v205
	s_nop 0
	v_cvt_pk_bf16_f32 v205, v206, v207
	v_pk_mul_f32 v[206:207], v[24:25], v[190:191] op_sel_hi:[1,0]
	s_nop 0
	v_cvt_pk_bf16_f32 v206, v206, v207
	v_cvt_pk_bf16_f32 v207, v208, v209
	v_mad_i64_i32 v[208:209], s[2:3], v174, s41, v[148:149]
	v_lshl_add_u64 v[208:209], v[208:209], 0, v[150:151]
	global_store_dwordx4 v[208:209], v[204:207], off
	v_mad_i64_i32 v[148:149], s[2:3], v170, s41, v[148:149]
	s_nop 0
	v_pk_mul_f32 v[204:205], v[20:21], v[190:191] op_sel_hi:[1,0]
	v_pk_mul_f32 v[206:207], v[22:23], v[190:191] op_sel_hi:[1,0]
	v_cvt_pk_bf16_f32 v204, v204, v205
	v_lshl_add_u64 v[148:149], v[148:149], 0, v[150:151]
	v_cvt_pk_bf16_f32 v205, v206, v207
	v_pk_mul_f32 v[206:207], v[16:17], v[190:191] op_sel_hi:[1,0]
	v_pk_mul_f32 v[190:191], v[18:19], v[190:191] op_sel_hi:[1,0]
	v_cvt_pk_bf16_f32 v206, v206, v207
	v_pk_mul_f32 v[150:151], v[6:7], v[188:189] op_sel_hi:[1,0]
	v_cvt_pk_bf16_f32 v207, v190, v191
	global_store_dwordx4 v[208:209], v[204:207], off offset:256
	v_pk_mul_f32 v[208:209], v[10:11], v[188:189] op_sel_hi:[1,0]
	v_mad_i64_i32 v[190:191], s[2:3], v170, s41, 0
	v_pk_mul_f32 v[204:205], v[12:13], v[188:189] op_sel_hi:[1,0]
	v_pk_mul_f32 v[206:207], v[14:15], v[188:189] op_sel_hi:[1,0]
	v_cvt_pk_bf16_f32 v204, v204, v205
	s_nop 0
	v_cvt_pk_bf16_f32 v205, v206, v207
	v_pk_mul_f32 v[206:207], v[8:9], v[188:189] op_sel_hi:[1,0]
	s_nop 0
	v_cvt_pk_bf16_f32 v206, v206, v207
	v_cvt_pk_bf16_f32 v207, v208, v209
	global_store_dwordx4 v[148:149], v[204:207], off
	v_pk_mul_f32 v[148:149], v[4:5], v[188:189] op_sel_hi:[1,0]
	s_nop 0
	v_cvt_pk_bf16_f32 v148, v148, v149
	v_cvt_pk_bf16_f32 v149, v150, v151
	v_pk_mul_f32 v[150:151], v[0:1], v[188:189] op_sel_hi:[1,0]
	v_pk_mul_f32 v[204:205], v[2:3], v[188:189] op_sel_hi:[1,0]
	v_cvt_pk_bf16_f32 v150, v150, v151
	s_nop 0
	v_cvt_pk_bf16_f32 v151, v204, v205
	s_cbranch_execz .LBB0_385
	s_branch .LBB0_386

; __device__ __forceinline__ unsigned cvt_pk_bf16(float lo, float hi) { unsigned r; asm volatile("v_cvt_pk_bf16_f32 %0, %1, %2" : "=v"(r) : "v"(lo), "v"(hi)); return r; }
;     template <bool GATE> __device__ __forceinline__ void body(const f32x4 (&acc)[2][2][4][2], const Unit& u, int wr, int wc, int fr, int fq) const {
;     ...
;             for (int m = 0; m < 4; ++m) {
;                 const int row = row0 + ai * HALF + m * 16; const float r = rs[ai][m], nrl = r * -1.44269504089f;
; #pragma unroll
;                 for (int bj = 0; bj < 2; ++bj) {
;                     unsigned pk[4];
; #pragma unroll
;                     for (int q = 0; q < 4; ++q) {
;                         const f32x4 va = acc[ai][bj][m][q >> 1]; const int e0 = 2 * (q & 1);
;                         const f32x2 v = (f32x2){va[e0], va[e0 + 1]};
;                         f32x2 o;
;                         if (GATE) { const f32x2 t = v * nrl; f32x2 ex; ex.x = __builtin_amdgcn_exp2f(t.x); ex.y = __builtin_amdgcn_exp2f(t.y);
;                             const f32x2 d = ex + 1.0f; o.x = __builtin_amdgcn_rcpf(d.x); o.y = __builtin_amdgcn_rcpf(d.y); }
;                         else o = v * r;
;                         pk[q] = cvt_pk_bf16(o.x, o.y);
;                     }
;                     u32x4 w; w.x = pk[0]; w.y = pk[1]; w.z = pk[2]; w.w = pk[3];
;                     *(u32x4*)(P + (size_t)row * PITCH + col0 + bj * HALF) = w;
rsc_hit_2:
	v_lshl_add_u32 v186, s33, 8, v193
	v_or_b32_e32 v184, 16, v186
	s_nop 3
	v_or_b32_e32 v182, 32, v186
	v_or_b32_e32 v180, 48, v186
	s_nop 4
	v_add_u32_e32 v178, 0x80, v186
	v_add_u32_e32 v176, 0x90, v186
	v_add_u32_e32 v174, 0xa0, v186
	v_add_u32_e32 v170, 0xb0, v186
	v_and_b32_e32 v172, 64, v201
	v_xor_b32_e32 v171, 16, v201
	v_add_u32_e32 v172, 64, v172
	v_xor_b32_e32 v173, 32, v201
	v_cmp_lt_i32_e32 vcc, v171, v172
	s_cmp_lt_i32 s43, 9
	v_lshl_or_b32 v160, s43, 8, v197
	v_cndmask_b32_e32 v171, v201, v171, vcc
	v_cmp_lt_i32_e32 vcc, v173, v172
	v_lshlrev_b32_e32 v175, 2, v171
	s_nop 2
	v_cndmask_b32_e32 v172, v201, v173, vcc
	s_nop 2
	v_lshlrev_b32_e32 v171, 2, v172
	s_cbranch_scc0 rsc_hitb_2
	v_mov_b32_e32 v208, v240
	v_mov_b32_e32 v210, v241
	v_mov_b32_e32 v212, v242
	v_mov_b32_e32 v214, v243
	v_mov_b32_e32 v194, v244
	v_mov_b32_e32 v192, v245
	v_mov_b32_e32 v190, v246
	v_mov_b32_e32 v188, v247
	s_waitcnt lgkmcnt(0)
	v_pk_mul_f32 v[148:149], v[124:125], v[208:209] op_sel_hi:[1,0]
	v_readlane_b32 s2, v235, 44
	v_cvt_pk_bf16_f32 v204, v148, v149
	v_pk_mul_f32 v[148:149], v[126:127], v[208:209] op_sel_hi:[1,0]
	v_readlane_b32 s3, v235, 45
	v_cvt_pk_bf16_f32 v205, v148, v149
	v_pk_mul_f32 v[148:149], v[120:121], v[208:209] op_sel_hi:[1,0]
	v_ashrrev_i32_e32 v173, 31, v160
	v_cvt_pk_bf16_f32 v206, v148, v149
	v_pk_mul_f32 v[148:149], v[122:123], v[208:209] op_sel_hi:[1,0]
	v_mov_b32_e32 v172, v160
	v_cvt_pk_bf16_f32 v207, v148, v149
	v_mov_b64_e32 v[148:149], s[2:3]
	v_mad_i64_i32 v[216:217], s[2:3], v186, s41, v[148:149]
	v_lshlrev_b64 v[150:151], 1, v[172:173]
	v_lshl_add_u64 v[216:217], v[216:217], 0, v[150:151]
	global_store_dwordx4 v[216:217], v[204:207], off
	s_and_b64 vcc, exec, s[8:9]
	s_cbranch_vccz late_align_8
	s_barrier
late_align_8:
	s_branch late_after_7
rsc_hitb_2:
	v_mov_b64_e32 v[172:173], v[160:161]
	v_readlane_b32 s2, v235, 44
	v_mov_b32_e32 v132, v240
	s_nop 0
	v_mov_b32_e32 v133, v241
	s_nop 0
	v_mul_f32_e32 v132, 0xbfb8aa3b, v132
	v_mov_b32_e32 v136, v242
	v_pk_mul_f32 v[124:125], v[124:125], v[132:133] op_sel_hi:[1,0]
	v_pk_mul_f32 v[120:121], v[120:121], v[132:133] op_sel_hi:[1,0]
	v_exp_f32_e32 v124, v124
	v_exp_f32_e32 v125, v125
	v_pk_mul_f32 v[126:127], v[126:127], v[132:133] op_sel_hi:[1,0]
	v_exp_f32_e32 v120, v120
	v_exp_f32_e32 v121, v121
	v_pk_mul_f32 v[122:123], v[122:123], v[132:133] op_sel_hi:[1,0]
	v_exp_f32_e32 v126, v126
	v_exp_f32_e32 v127, v127
	v_exp_f32_e32 v122, v122
	v_exp_f32_e32 v123, v123
	v_mov_b32_e32 v137, v243
	v_mov_b32_e32 v138, v244
	v_pk_add_f32 v[124:125], v[124:125], 1.0 op_sel_hi:[1,0]
	v_pk_add_f32 v[120:121], v[120:121], 1.0 op_sel_hi:[1,0]
	v_pk_mul_f32 v[116:117], v[116:117], v[132:133] op_sel_hi:[1,0]
	v_pk_mul_f32 v[112:113], v[112:113], v[132:133] op_sel_hi:[1,0]
	v_mov_b32_e32 v130, v245
	s_nop 0
	v_rcp_f32_e32 v131, v124
	v_rcp_f32_e32 v134, v125
	v_pk_add_f32 v[124:125], v[126:127], 1.0 op_sel_hi:[1,0]
	v_rcp_f32_e32 v127, v120
	v_rcp_f32_e32 v135, v121
	v_pk_add_f32 v[120:121], v[122:123], 1.0 op_sel_hi:[1,0]
	v_exp_f32_e32 v116, v116
	v_exp_f32_e32 v117, v117
	v_pk_mul_f32 v[118:119], v[118:119], v[132:133] op_sel_hi:[1,0]
	v_exp_f32_e32 v112, v112
	v_exp_f32_e32 v113, v113
	v_pk_mul_f32 v[114:115], v[114:115], v[132:133] op_sel_hi:[1,0]
	v_rcp_f32_e32 v126, v124
	v_rcp_f32_e32 v125, v125
	v_rcp_f32_e32 v120, v120
	v_rcp_f32_e32 v121, v121
	v_readlane_b32 s3, v235, 45
	v_exp_f32_e32 v118, v118
	v_exp_f32_e32 v119, v119
	v_exp_f32_e32 v114, v114
	v_exp_f32_e32 v115, v115
	v_cvt_pk_bf16_f32 v124, v131, v134
	v_cvt_pk_bf16_f32 v125, v126, v125
	v_cvt_pk_bf16_f32 v126, v127, v135
	v_cvt_pk_bf16_f32 v127, v120, v121
	v_mov_b64_e32 v[120:121], s[2:3]
	v_mad_i64_i32 v[134:135], s[2:3], v186, s41, v[120:121]
	v_lshlrev_b64 v[122:123], 1, v[160:161]
	v_lshl_add_u64 v[134:135], v[134:135], 0, v[122:123]
	v_pk_add_f32 v[116:117], v[116:117], 1.0 op_sel_hi:[1,0]
	v_pk_add_f32 v[112:113], v[112:113], 1.0 op_sel_hi:[1,0]
	global_store_dwordx4 v[134:135], v[124:127], off
	s_and_b64 vcc, exec, s[8:9]
	s_cbranch_vccz late_align_9
	s_barrier
late_align_9:
	v_mov_b32_e32 v129, v246
	s_nop 0
	v_rcp_f32_e32 v124, v116
	v_rcp_f32_e32 v125, v117
	v_pk_add_f32 v[116:117], v[118:119], 1.0 op_sel_hi:[1,0]
	v_rcp_f32_e32 v118, v112
	v_rcp_f32_e32 v119, v113
	v_pk_add_f32 v[112:113], v[114:115], 1.0 op_sel_hi:[1,0]
	v_rcp_f32_e32 v116, v116
	v_rcp_f32_e32 v115, v112
	v_cvt_pk_bf16_f32 v112, v124, v125
	v_rcp_f32_e32 v117, v117
	v_rcp_f32_e32 v126, v113
	v_cvt_pk_bf16_f32 v113, v116, v117
	v_cvt_pk_bf16_f32 v114, v118, v119
	v_cvt_pk_bf16_f32 v115, v115, v126
	global_store_dwordx4 v[134:135], v[112:115], off offset:256
	v_mov_b32_e32 v128, v247
	s_waitcnt lgkmcnt(0)
	s_branch rsc_joinb_2

; __device__ __forceinline__ unsigned cvt_pk_bf16(float lo, float hi) { unsigned r; asm volatile("v_cvt_pk_bf16_f32 %0, %1, %2" : "=v"(r) : "v"(lo), "v"(hi)); return r; }
; template <int NP> __device__ __forceinline__ void load_rs(const float* ssp, int row0, int fq, float (&rs)[2][4]) {
;     ...
;     } else {
;         f32x4 p[2][4];
; #pragma unroll
;         for (int ai = 0; ai < 2; ++ai)
; #pragma unroll
;             for (int m = 0; m < 4; ++m) p[ai][m] = *(const f32x4*)(ssp + (size_t)(row0 + ai * HALF + m * 16) * 16 + 4 * fq);
;     __device__ __forceinline__ void operator()(const f32x4 (&acc)[2][2][4][2], const Unit& u, int wr, int wc, int fr, int fq) const {
;         const int row0 = u.pm * BM + wr * 64 + fr, col0 = u.pn * HALF + wc * 32 + 8 * fq;
;         float rs[2][4]; load_rs<NP>(ssp, row0, fq, rs);
; #pragma unroll
;         for (int ai = 0; ai < 2; ++ai)
; #pragma unroll
;             for (int m = 0; m < 4; ++m) {
;                 const int row = row0 + ai * HALF + m * 16; const float r = rs[ai][m];
;                 const float nrl = r * -1.44269504089f, r2 = r * r;
;                 unsigned pk[4];
; #pragma unroll
;                 for (int q = 0; q < 4; ++q) {
;                     const f32x4 ga = acc[ai][0][m][q >> 1], ua = acc[ai][1][m][q >> 1]; const int e0 = 2 * (q & 1);
;                     const f32x2 g = (f32x2){ga[e0], ga[e0 + 1]}, up = (f32x2){ua[e0], ua[e0 + 1]};
;                     const f32x2 t = g * nrl; f32x2 ex; ex.x = __builtin_amdgcn_exp2f(t.x); ex.y = __builtin_amdgcn_exp2f(t.y);
;                     const f32x2 d = ex + 1.0f; f32x2 rc; rc.x = __builtin_amdgcn_rcpf(d.x); rc.y = __builtin_amdgcn_rcpf(d.y);
;                     const f32x2 o = (g * up) * (rc * r2);
;                     pk[q] = cvt_pk_bf16(o.x, o.y);
;                 }
;                 u32x4 w; w.x = pk[0]; w.y = pk[1]; w.z = pk[2]; w.w = pk[3];
;                 *(u32x4*)(U + (size_t)(row >> 13) * U_SLAB + (size_t)(row & (SEQ - 1)) * U_PITCH + col0) = w;
.LBB0_932:
	v_cmp_eq_u32_e32 vcc, s41, v248
	s_cbranch_vccnz rsc_hit_1
	s_lshl_b32 s2, s41, 8
	s_add_i32 s2, s2, s29
	v_or_b32_e32 v146, s2, v150
	v_ashrrev_i32_e32 v147, 31, v146
	v_or_b32_e32 v160, 16, v146
	v_lshlrev_b64 v[148:149], 6, v[146:147]
	v_ashrrev_i32_e32 v161, 31, v160
	v_or_b32_e32 v168, 32, v146
	v_or_b32_e32 v170, 48, v146
	v_add_u32_e32 v146, 0x80, v146
	v_lshlrev_b64 v[160:161], 6, v[160:161]
	v_ashrrev_i32_e32 v169, 31, v168
	v_ashrrev_i32_e32 v171, 31, v170
	v_ashrrev_i32_e32 v147, 31, v146
	v_lshl_add_u64 v[148:149], v[138:139], 0, v[148:149]
	v_lshl_add_u64 v[164:165], v[138:139], 0, v[160:161]
	v_lshlrev_b64 v[168:169], 6, v[168:169]
	v_lshlrev_b64 v[170:171], 6, v[170:171]
	v_lshlrev_b64 v[176:177], 6, v[146:147]
	global_load_dwordx4 v[160:163], v[148:149], off
	s_nop 0
	global_load_dwordx4 v[164:167], v[164:165], off
	v_lshl_add_u64 v[168:169], v[138:139], 0, v[168:169]
	v_lshl_add_u64 v[172:173], v[138:139], 0, v[170:171]
	v_lshl_add_u64 v[176:177], v[138:139], 0, v[176:177]
	global_load_dwordx4 v[168:171], v[168:169], off
	s_nop 0
	global_load_dwordx4 v[172:175], v[172:173], off
	v_add_co_u32_e32 v148, vcc, s26, v148
	global_load_dwordx4 v[176:179], v[176:177], off
	s_nop 0
	v_addc_co_u32_e32 v149, vcc, 0, v149, vcc
	global_load_dwordx4 v[180:183], v[148:149], off offset:1024
	global_load_dwordx4 v[184:187], v[148:149], off offset:2048
	global_load_dwordx4 v[190:193], v[148:149], off offset:3072
	v_and_b32_e32 v147, 64, v156
	v_xor_b32_e32 v136, 16, v156
	v_add_u32_e32 v147, 64, v147
	v_xor_b32_e32 v149, 32, v156
	v_cmp_lt_i32_e32 vcc, v136, v147
	v_pk_mul_f32 v[120:121], v[124:125], v[120:121]
	v_pk_mul_f32 v[122:123], v[126:127], v[122:123]
	v_cndmask_b32_e32 v136, v156, v136, vcc
	v_cmp_lt_i32_e32 vcc, v149, v147
	v_lshlrev_b32_e32 v136, 2, v136
	v_pk_mul_f32 v[112:113], v[116:117], v[112:113]
	v_cndmask_b32_e32 v147, v156, v149, vcc
	v_lshlrev_b32_e32 v147, 2, v147
	v_pk_mul_f32 v[114:115], v[118:119], v[114:115]
	v_pk_mul_f32 v[104:105], v[108:109], v[104:105]
	s_ashr_i32 s3, s2, 13
	s_mul_hi_i32 s11, s3, 0x4400000
	s_mul_i32 s3, s3, 0x4400000
	v_readlane_b32 s16, v235, 44
	v_lshl_or_b32 v148, s42, 7, v152
	v_readlane_b32 s17, v235, 45
	v_pk_mul_f32 v[106:107], v[110:111], v[106:107]
	v_pk_mul_f32 v[96:97], v[100:101], v[96:97]
	v_pk_mul_f32 v[98:99], v[102:103], v[98:99]
	v_pk_mul_f32 v[88:89], v[92:93], v[88:89]
	v_pk_mul_f32 v[90:91], v[94:95], v[90:91]
	v_pk_mul_f32 v[80:81], v[84:85], v[80:81]
	v_pk_mul_f32 v[82:83], v[86:87], v[82:83]
	v_pk_mul_f32 v[72:73], v[76:77], v[72:73]
	v_pk_mul_f32 v[74:75], v[78:79], v[74:75]
	v_pk_mul_f32 v[64:65], v[68:69], v[64:65]
	v_pk_mul_f32 v[66:67], v[70:71], v[66:67]
	v_pk_mul_f32 v[56:57], v[60:61], v[56:57]
	v_pk_mul_f32 v[58:59], v[62:63], v[58:59]
	v_pk_mul_f32 v[48:49], v[52:53], v[48:49]
	v_pk_mul_f32 v[50:51], v[54:55], v[50:51]
	v_pk_mul_f32 v[40:41], v[44:45], v[40:41]
	v_pk_mul_f32 v[42:43], v[46:47], v[42:43]
	v_pk_mul_f32 v[32:33], v[36:37], v[32:33]
	v_pk_mul_f32 v[34:35], v[38:39], v[34:35]
	v_pk_mul_f32 v[24:25], v[28:29], v[24:25]
	v_pk_mul_f32 v[26:27], v[30:31], v[26:27]
	v_pk_mul_f32 v[16:17], v[20:21], v[16:17]
	v_pk_mul_f32 v[18:19], v[22:23], v[18:19]
	v_pk_mul_f32 v[8:9], v[12:13], v[8:9]
	v_pk_mul_f32 v[10:11], v[14:15], v[10:11]
	v_pk_mul_f32 v[0:1], v[4:5], v[0:1]
	v_pk_mul_f32 v[2:3], v[6:7], v[2:3]
	s_and_b64 vcc, exec, s[8:9]
	s_cbranch_vccz late_align_1
	s_barrier
late_align_1:
	s_waitcnt vmcnt(0)
	v_mov_b32_e32 v194, v161
	v_mov_b32_e32 v195, v162
	v_mov_b32_e32 v161, v163
	v_pk_add_f32 v[160:161], v[194:195], v[160:161]
	v_mov_b32_e32 v162, v165
	v_mov_b32_e32 v163, v166
	v_mov_b32_e32 v165, v167
	v_mov_b32_e32 v166, v169
	v_mov_b32_e32 v167, v170
	v_mov_b32_e32 v169, v171
	v_mov_b32_e32 v170, v173
	v_mov_b32_e32 v171, v174
	v_mov_b32_e32 v173, v175
	v_mov_b32_e32 v174, v177
	v_mov_b32_e32 v175, v178
	v_mov_b32_e32 v177, v179
	v_add_f32_e32 v149, v160, v161
	v_pk_add_f32 v[160:161], v[162:163], v[164:165]
	v_pk_add_f32 v[162:163], v[166:167], v[168:169]
	v_pk_add_f32 v[166:167], v[174:175], v[176:177]
	v_add_f32_e32 v160, v160, v161
	v_add_f32_e32 v161, v162, v163
	v_mov_b32_e32 v236, v149
	v_mov_b32_e32 v237, v149
	s_nop 1
	v_permlane16_swap_b32_e32 v236, v237
	v_cndmask_b32_e64 v159, v237, v236, s[98:99]
	v_add_f32_e32 v163, v166, v167
	v_mov_b32_e32 v236, v160
	v_mov_b32_e32 v237, v160
	s_nop 1
	v_permlane16_swap_b32_e32 v236, v237
	v_cndmask_b32_e64 v166, v237, v236, s[98:99]
	v_mov_b32_e32 v236, v161
	v_mov_b32_e32 v237, v161
	s_nop 1
	v_permlane16_swap_b32_e32 v236, v237
	v_cndmask_b32_e64 v167, v237, v236, s[98:99]
	v_mov_b32_e32 v178, v181
	s_waitcnt lgkmcnt(2)
	v_add_f32_e32 v149, v149, v159
	v_mov_b32_e32 v236, v149
	v_mov_b32_e32 v237, v149
	s_nop 1
	v_permlane32_swap_b32_e32 v236, v237
	v_cndmask_b32_e64 v159, v237, v236, s[100:101]
	s_waitcnt lgkmcnt(2)
	v_add_f32_e32 v160, v160, v166
	s_waitcnt lgkmcnt(1)
	v_add_f32_e32 v161, v161, v167
	v_mov_b32_e32 v236, v160
	v_mov_b32_e32 v237, v160
	s_nop 1
	v_permlane32_swap_b32_e32 v236, v237
	v_cndmask_b32_e64 v166, v237, v236, s[100:101]
	v_mov_b32_e32 v236, v161
	v_mov_b32_e32 v237, v161
	s_nop 1
	v_permlane32_swap_b32_e32 v236, v237
	v_cndmask_b32_e64 v167, v237, v236, s[100:101]
	v_mov_b32_e32 v179, v182
	v_mov_b32_e32 v181, v183
	v_mov_b32_e32 v182, v185
	v_mov_b32_e32 v183, v186
	v_mov_b32_e32 v185, v187
	v_mov_b32_e32 v186, v191
	v_mov_b32_e32 v187, v192
	v_mov_b32_e32 v191, v193
	v_pk_add_f32 v[164:165], v[170:171], v[172:173]
	v_pk_add_f32 v[168:169], v[178:179], v[180:181]
	v_pk_add_f32 v[170:171], v[182:183], v[184:185]
	s_waitcnt lgkmcnt(2)
; template <int NP> __device__ __forceinline__ void load_rs(const float* ssp, int row0, int fq, float (&rs)[2][4]) {
;     ...
; #pragma unroll
;         for (int ai = 0; ai < 2; ++ai)
; #pragma unroll
;             for (int m = 0; m < 4; ++m) { float s = (p[ai][m][0] + p[ai][m][1]) + (p[ai][m][2] + p[ai][m][3]); s += __shfl_xor(s, 16); s += __shfl_xor(s, 32); rs[ai][m] = s; }
;     }
; #pragma unroll
;     for (int ai = 0; ai < 2; ++ai)
; #pragma unroll
;         for (int m = 0; m < 4; ++m) rs[ai][m] = __builtin_amdgcn_rsqf(rs[ai][m] * (1.0f / D_MODEL) + RMS_EPS);
	v_add_f32_e32 v149, v149, v159
	s_waitcnt lgkmcnt(1)
	v_add_f32_e32 v159, v160, v166
	s_waitcnt lgkmcnt(0)
	v_add_f32_e32 v166, v161, v167
	v_pk_add_f32 v[160:161], v[186:187], v[190:191]
	v_add_f32_e32 v162, v164, v165
	v_add_f32_e32 v164, v168, v169
	v_add_f32_e32 v165, v170, v171
	v_add_f32_e32 v160, v160, v161
	v_mov_b32_e32 v236, v162
	v_mov_b32_e32 v237, v162
	s_nop 1
	v_permlane16_swap_b32_e32 v236, v237
	v_cndmask_b32_e64 v168, v237, v236, s[98:99]
	v_mov_b32_e32 v236, v163
	v_mov_b32_e32 v237, v163
	s_nop 1
	v_permlane16_swap_b32_e32 v236, v237
	v_cndmask_b32_e64 v169, v237, v236, s[98:99]
	v_mov_b32_e32 v236, v164
	v_mov_b32_e32 v237, v164
	s_nop 1
	v_permlane16_swap_b32_e32 v236, v237
	v_cndmask_b32_e64 v170, v237, v236, s[98:99]
	v_mov_b32_e32 v236, v165
	v_mov_b32_e32 v237, v165
	s_nop 1
	v_permlane16_swap_b32_e32 v236, v237
	v_cndmask_b32_e64 v171, v237, v236, s[98:99]
	v_mov_b32_e32 v236, v160
	v_mov_b32_e32 v237, v160
	s_nop 1
	v_permlane16_swap_b32_e32 v236, v237
	v_cndmask_b32_e64 v136, v237, v236, s[98:99]
	s_waitcnt lgkmcnt(4)
	v_add_f32_e32 v162, v162, v168
	s_waitcnt lgkmcnt(3)
	v_add_f32_e32 v163, v163, v169
	s_waitcnt lgkmcnt(2)
	v_add_f32_e32 v161, v164, v170
	s_waitcnt lgkmcnt(1)
	v_add_f32_e32 v165, v165, v171
	s_waitcnt lgkmcnt(0)
	v_add_f32_e32 v136, v160, v136
	v_mov_b32_e32 v236, v162
	v_mov_b32_e32 v237, v162
	s_nop 1
	v_permlane32_swap_b32_e32 v236, v237
	v_cndmask_b32_e64 v168, v237, v236, s[100:101]
	v_mov_b32_e32 v236, v163
	v_mov_b32_e32 v237, v163
	s_nop 1
	v_permlane32_swap_b32_e32 v236, v237
	v_cndmask_b32_e64 v169, v237, v236, s[100:101]
	v_mov_b32_e32 v236, v161
	v_mov_b32_e32 v237, v161
	s_nop 1
	v_permlane32_swap_b32_e32 v236, v237
	v_cndmask_b32_e64 v164, v237, v236, s[100:101]
	v_mov_b32_e32 v236, v165
	v_mov_b32_e32 v237, v165
	s_nop 1
	v_permlane32_swap_b32_e32 v236, v237
	v_cndmask_b32_e64 v167, v237, v236, s[100:101]
	v_mov_b32_e32 v236, v136
	v_mov_b32_e32 v237, v136
	s_nop 1
	v_permlane32_swap_b32_e32 v236, v237
	v_cndmask_b32_e64 v147, v237, v236, s[100:101]
	s_waitcnt lgkmcnt(4)
	v_add_f32_e32 v160, v162, v168
	s_waitcnt lgkmcnt(3)
	v_add_f32_e32 v162, v163, v169
	s_waitcnt lgkmcnt(2)
	v_add_f32_e32 v161, v161, v164
	s_waitcnt lgkmcnt(1)
	v_add_f32_e32 v163, v165, v167
	s_waitcnt lgkmcnt(0)
	v_add_f32_e32 v136, v136, v147
	v_fmamk_f32 v147, v149, 0x3a800000, v157
	v_rsq_f32_e32 v164, v147
	s_nop 0
	v_mov_b32_e32 v240, v164
	v_fmamk_f32 v147, v159, 0x3a800000, v157
	v_rsq_f32_e32 v165, v147
	s_nop 0
	v_mov_b32_e32 v241, v165
	v_fmamk_f32 v147, v166, 0x3a800000, v157
	v_rsq_f32_e32 v166, v147
	s_nop 0
	v_mov_b32_e32 v242, v166
	v_fmamk_f32 v147, v160, 0x3a800000, v157
	v_rsq_f32_e32 v167, v147
	s_nop 0
	v_mov_b32_e32 v243, v167
	v_fmamk_f32 v147, v162, 0x3a800000, v157
	v_rsq_f32_e32 v168, v147
	s_nop 0
	v_mov_b32_e32 v244, v168
	v_fmamk_f32 v147, v161, 0x3a800000, v157
	v_rsq_f32_e32 v160, v147
	s_nop 0
	v_mov_b32_e32 v245, v160
	v_fmamk_f32 v147, v163, 0x3a800000, v157
	v_fmamk_f32 v136, v136, 0x3a800000, v157
	v_rsq_f32_e32 v159, v147
	s_nop 0
	v_mov_b32_e32 v246, v159
	v_rsq_f32_e32 v147, v136
	s_nop 0
	v_mov_b32_e32 v247, v147
	v_mov_b32_e32 v248, s41
	s_branch rsc_join_1
; __device__ __forceinline__ unsigned cvt_pk_bf16(float lo, float hi) { unsigned r; asm volatile("v_cvt_pk_bf16_f32 %0, %1, %2" : "=v"(r) : "v"(lo), "v"(hi)); return r; }
;     __device__ __forceinline__ void operator()(const f32x4 (&acc)[2][2][4][2], const Unit& u, int wr, int wc, int fr, int fq) const {
;     ...
;         for (int ai = 0; ai < 2; ++ai)
; #pragma unroll
;             for (int m = 0; m < 4; ++m) {
;                 const int row = row0 + ai * HALF + m * 16; const float r = rs[ai][m];
;                 const float nrl = r * -1.44269504089f, r2 = r * r;
;                 unsigned pk[4];
; #pragma unroll
;                 for (int q = 0; q < 4; ++q) {
;                     const f32x4 ga = acc[ai][0][m][q >> 1], ua = acc[ai][1][m][q >> 1]; const int e0 = 2 * (q & 1);
;                     const f32x2 g = (f32x2){ga[e0], ga[e0 + 1]}, up = (f32x2){ua[e0], ua[e0 + 1]};
;                     const f32x2 t = g * nrl; f32x2 ex; ex.x = __builtin_amdgcn_exp2f(t.x); ex.y = __builtin_amdgcn_exp2f(t.y);
;                     const f32x2 d = ex + 1.0f; f32x2 rc; rc.x = __builtin_amdgcn_rcpf(d.x); rc.y = __builtin_amdgcn_rcpf(d.y);
;                     const f32x2 o = (g * up) * (rc * r2);
;                     pk[q] = cvt_pk_bf16(o.x, o.y);
;                 }
;                 u32x4 w; w.x = pk[0]; w.y = pk[1]; w.z = pk[2]; w.w = pk[3];
;                 *(u32x4*)(U + (size_t)(row >> 13) * U_SLAB + (size_t)(row & (SEQ - 1)) * U_PITCH + col0) = w;
rsc_hit_1:
	s_lshl_b32 s2, s41, 8
	s_add_i32 s2, s2, s29
	v_or_b32_e32 v146, s2, v150
	s_nop 4
	v_add_u32_e32 v146, 0x80, v146
	v_pk_mul_f32 v[120:121], v[124:125], v[120:121]
	v_pk_mul_f32 v[122:123], v[126:127], v[122:123]
	v_pk_mul_f32 v[112:113], v[116:117], v[112:113]
	v_pk_mul_f32 v[114:115], v[118:119], v[114:115]
	v_pk_mul_f32 v[104:105], v[108:109], v[104:105]
	s_ashr_i32 s3, s2, 13
	s_mul_hi_i32 s11, s3, 0x4400000
	s_mul_i32 s3, s3, 0x4400000
	v_readlane_b32 s16, v235, 44
	v_lshl_or_b32 v148, s42, 7, v152
	v_readlane_b32 s17, v235, 45
	v_pk_mul_f32 v[106:107], v[110:111], v[106:107]
	v_pk_mul_f32 v[96:97], v[100:101], v[96:97]
	v_pk_mul_f32 v[98:99], v[102:103], v[98:99]
	v_pk_mul_f32 v[88:89], v[92:93], v[88:89]
	v_pk_mul_f32 v[90:91], v[94:95], v[90:91]
	v_pk_mul_f32 v[80:81], v[84:85], v[80:81]
	v_pk_mul_f32 v[82:83], v[86:87], v[82:83]
	v_pk_mul_f32 v[72:73], v[76:77], v[72:73]
	v_pk_mul_f32 v[74:75], v[78:79], v[74:75]
	v_pk_mul_f32 v[64:65], v[68:69], v[64:65]
	v_pk_mul_f32 v[66:67], v[70:71], v[66:67]
	v_pk_mul_f32 v[56:57], v[60:61], v[56:57]
	v_pk_mul_f32 v[58:59], v[62:63], v[58:59]
	v_pk_mul_f32 v[48:49], v[52:53], v[48:49]
	v_pk_mul_f32 v[50:51], v[54:55], v[50:51]
	v_pk_mul_f32 v[40:41], v[44:45], v[40:41]
	v_pk_mul_f32 v[42:43], v[46:47], v[42:43]
	v_pk_mul_f32 v[32:33], v[36:37], v[32:33]
	v_pk_mul_f32 v[34:35], v[38:39], v[34:35]
	v_pk_mul_f32 v[24:25], v[28:29], v[24:25]
	v_pk_mul_f32 v[26:27], v[30:31], v[26:27]
	v_pk_mul_f32 v[16:17], v[20:21], v[16:17]
	v_pk_mul_f32 v[18:19], v[22:23], v[18:19]
	v_pk_mul_f32 v[8:9], v[12:13], v[8:9]
	v_pk_mul_f32 v[10:11], v[14:15], v[10:11]
	v_pk_mul_f32 v[0:1], v[4:5], v[0:1]
	v_pk_mul_f32 v[2:3], v[6:7], v[2:3]
	v_mov_b32_e32 v164, v240
	v_mov_b32_e32 v165, v241
	v_mov_b32_e32 v166, v242
	v_mov_b32_e32 v167, v243
	v_mov_b32_e32 v168, v244
	v_mov_b32_e32 v160, v245
	v_mov_b32_e32 v159, v246
	v_mov_b32_e32 v147, v247
	s_waitcnt lgkmcnt(0)
	v_mul_f32_e32 v136, 0xbfb8aa3b, v164
	v_pk_mul_f32 v[162:163], v[124:125], v[136:137] op_sel_hi:[1,0]
	v_pk_mul_f32 v[124:125], v[126:127], v[136:137] op_sel_hi:[1,0]
	v_exp_f32_e32 v162, v162
	v_exp_f32_e32 v163, v163
	v_exp_f32_e32 v124, v124
	v_exp_f32_e32 v125, v125
	v_mul_f32_e32 v164, v164, v164
	v_pk_add_f32 v[162:163], v[162:163], 1.0 op_sel_hi:[1,0]
	v_bitop3_b32 v161, s2, v158, v150 bitop3:0xc8
	v_rcp_f32_e32 v162, v162
	v_rcp_f32_e32 v163, v163
	v_pk_add_f32 v[124:125], v[124:125], 1.0 op_sel_hi:[1,0]
	s_add_u32 s2, s16, s3
	v_rcp_f32_e32 v124, v124
	v_rcp_f32_e32 v125, v125
	v_pk_mul_f32 v[126:127], v[164:165], v[162:163] op_sel_hi:[0,1]
	v_pk_mul_f32 v[120:121], v[120:121], v[126:127]
	v_pk_mul_f32 v[126:127], v[116:117], v[136:137] op_sel_hi:[1,0]
	v_pk_mul_f32 v[124:125], v[164:165], v[124:125] op_sel_hi:[0,1]
	v_exp_f32_e32 v126, v126
	v_exp_f32_e32 v127, v127
	v_pk_mul_f32 v[122:123], v[122:123], v[124:125]
	v_pk_mul_f32 v[124:125], v[118:119], v[136:137] op_sel_hi:[1,0]
	v_cvt_pk_bf16_f32 v120, v120, v121
	v_cvt_pk_bf16_f32 v121, v122, v123
	v_pk_add_f32 v[122:123], v[126:127], 1.0 op_sel_hi:[1,0]
	v_exp_f32_e32 v124, v124
	v_exp_f32_e32 v125, v125
	v_rcp_f32_e32 v122, v122
	v_rcp_f32_e32 v123, v123
	v_ashrrev_i32_e32 v149, 31, v148
	v_pk_add_f32 v[116:117], v[124:125], 1.0 op_sel_hi:[1,0]
	s_addc_u32 s3, s17, s11
	v_rcp_f32_e32 v116, v116
	v_rcp_f32_e32 v117, v117
	v_pk_mul_f32 v[118:119], v[164:165], v[122:123] op_sel_hi:[0,1]
	v_pk_mul_f32 v[112:113], v[112:113], v[118:119]
	s_nop 0
	v_cvt_pk_bf16_f32 v122, v112, v113
	v_pk_mul_f32 v[112:113], v[164:165], v[116:117] op_sel_hi:[0,1]
	v_mul_f32_e32 v116, 0xbfb8aa3b, v165
	v_pk_mul_f32 v[118:119], v[108:109], v[116:117] op_sel_hi:[1,0]
	v_pk_mul_f32 v[108:109], v[110:111], v[116:117] op_sel_hi:[1,0]
	v_exp_f32_e32 v118, v118
	v_exp_f32_e32 v119, v119
	v_exp_f32_e32 v108, v108
	v_exp_f32_e32 v109, v109
	v_pk_mul_f32 v[112:113], v[114:115], v[112:113]
	v_pk_add_f32 v[118:119], v[118:119], 1.0 op_sel_hi:[1,0]
	v_cvt_pk_bf16_f32 v123, v112, v113
	v_mul_u32_u24_e32 v112, 0xb40, v161
	v_lshlrev_b32_e32 v136, 1, v112
	v_rcp_f32_e32 v118, v118
	v_rcp_f32_e32 v119, v119
	v_lshl_add_u64 v[114:115], s[2:3], 0, v[136:137]
	v_lshlrev_b64 v[112:113], 1, v[148:149]
	v_pk_add_f32 v[108:109], v[108:109], 1.0 op_sel_hi:[1,0]
	v_lshl_add_u64 v[114:115], v[114:115], 0, v[112:113]
	v_rcp_f32_e32 v108, v108
	v_rcp_f32_e32 v109, v109
	global_store_dwordx4 v[114:115], v[120:123], off
	s_and_b64 vcc, exec, s[8:9]
	s_cbranch_vccz late_align_3
	s_barrier
late_align_3:
	s_branch late_after_2

; __device__ __forceinline__ unsigned cvt_pk_bf16(float lo, float hi) { unsigned r; asm volatile("v_cvt_pk_bf16_f32 %0, %1, %2" : "=v"(r) : "v"(lo), "v"(hi)); return r; }
;     __device__ __forceinline__ void operator()(const f32x4 (&acc)[2][2][4][2], const Unit& u, int wr, int wc, int fr, int fq) const {
;     ...
;         for (int ai = 0; ai < 2; ++ai)
; #pragma unroll
;             for (int m = 0; m < 4; ++m) {
;                 const int row = row0 + ai * HALF + m * 16; const float r = rs[ai][m];
;                 const float nrl = r * -1.44269504089f, r2 = r * r;
;                 unsigned pk[4];
; #pragma unroll
;                 for (int q = 0; q < 4; ++q) {
;                     const f32x4 ga = acc[ai][0][m][q >> 1], ua = acc[ai][1][m][q >> 1]; const int e0 = 2 * (q & 1);
;                     const f32x2 g = (f32x2){ga[e0], ga[e0 + 1]}, up = (f32x2){ua[e0], ua[e0 + 1]};
;                     const f32x2 t = g * nrl; f32x2 ex; ex.x = __builtin_amdgcn_exp2f(t.x); ex.y = __builtin_amdgcn_exp2f(t.y);
;                     const f32x2 d = ex + 1.0f; f32x2 rc; rc.x = __builtin_amdgcn_rcpf(d.x); rc.y = __builtin_amdgcn_rcpf(d.y);
;                     const f32x2 o = (g * up) * (rc * r2);
;                     pk[q] = cvt_pk_bf16(o.x, o.y);
;                 }
;                 u32x4 w; w.x = pk[0]; w.y = pk[1]; w.z = pk[2]; w.w = pk[3];
;                 *(u32x4*)(U + (size_t)(row >> 13) * U_SLAB + (size_t)(row & (SEQ - 1)) * U_PITCH + col0) = w;
late_after_2:
	s_nop 1
	v_mul_f32_e32 v120, v165, v165
	v_pk_mul_f32 v[110:111], v[120:121], v[118:119] op_sel_hi:[0,1]
	v_pk_mul_f32 v[104:105], v[104:105], v[110:111]
	v_pk_mul_f32 v[110:111], v[100:101], v[116:117] op_sel_hi:[1,0]
	v_pk_mul_f32 v[108:109], v[120:121], v[108:109] op_sel_hi:[0,1]
	v_exp_f32_e32 v110, v110
	v_exp_f32_e32 v111, v111
	v_pk_mul_f32 v[106:107], v[106:107], v[108:109]
	v_pk_mul_f32 v[108:109], v[102:103], v[116:117] op_sel_hi:[1,0]
	v_cvt_pk_bf16_f32 v104, v104, v105
	v_cvt_pk_bf16_f32 v105, v106, v107
	v_pk_add_f32 v[106:107], v[110:111], 1.0 op_sel_hi:[1,0]
	v_exp_f32_e32 v108, v108
	v_exp_f32_e32 v109, v109
	v_rcp_f32_e32 v106, v106
	v_rcp_f32_e32 v107, v107
	v_pk_add_f32 v[100:101], v[108:109], 1.0 op_sel_hi:[1,0]
	s_nop 0
	v_rcp_f32_e32 v100, v100
	v_rcp_f32_e32 v101, v101
	v_pk_mul_f32 v[102:103], v[120:121], v[106:107] op_sel_hi:[0,1]
	v_pk_mul_f32 v[96:97], v[96:97], v[102:103]
	s_nop 0
	v_cvt_pk_bf16_f32 v106, v96, v97
	v_pk_mul_f32 v[96:97], v[120:121], v[100:101] op_sel_hi:[0,1]
	v_pk_mul_f32 v[96:97], v[98:99], v[96:97]
	v_add_co_u32_e32 v100, vcc, s28, v114
	v_cvt_pk_bf16_f32 v107, v96, v97
	v_mul_f32_e32 v96, 0xbfb8aa3b, v166
	v_pk_mul_f32 v[98:99], v[92:93], v[96:97] op_sel_hi:[1,0]
	v_pk_mul_f32 v[92:93], v[94:95], v[96:97] op_sel_hi:[1,0]
	v_exp_f32_e32 v98, v98
	v_exp_f32_e32 v99, v99
	v_exp_f32_e32 v92, v92
	v_exp_f32_e32 v93, v93
	v_addc_co_u32_e32 v101, vcc, 0, v115, vcc
	v_pk_add_f32 v[98:99], v[98:99], 1.0 op_sel_hi:[1,0]
	v_pk_add_f32 v[92:93], v[92:93], 1.0 op_sel_hi:[1,0]
	v_rcp_f32_e32 v98, v98
	v_rcp_f32_e32 v99, v99
	v_rcp_f32_e32 v92, v92
	v_rcp_f32_e32 v93, v93
	global_store_dwordx4 v[100:101], v[104:107], off offset:2048
	v_mul_f32_e32 v100, v166, v166
	v_pk_mul_f32 v[94:95], v[100:101], v[98:99] op_sel_hi:[0,1]
	v_pk_mul_f32 v[88:89], v[88:89], v[94:95]
	v_pk_mul_f32 v[94:95], v[84:85], v[96:97] op_sel_hi:[1,0]
	v_pk_mul_f32 v[92:93], v[100:101], v[92:93] op_sel_hi:[0,1]
	v_exp_f32_e32 v94, v94
	v_exp_f32_e32 v95, v95
	v_pk_mul_f32 v[90:91], v[90:91], v[92:93]
	v_pk_mul_f32 v[92:93], v[86:87], v[96:97] op_sel_hi:[1,0]
	v_cvt_pk_bf16_f32 v88, v88, v89
	v_cvt_pk_bf16_f32 v89, v90, v91
	v_pk_add_f32 v[90:91], v[94:95], 1.0 op_sel_hi:[1,0]
	v_exp_f32_e32 v92, v92
	v_exp_f32_e32 v93, v93
	v_rcp_f32_e32 v90, v90
	v_rcp_f32_e32 v91, v91
	v_pk_add_f32 v[84:85], v[92:93], 1.0 op_sel_hi:[1,0]
	s_nop 0
	v_rcp_f32_e32 v84, v84
	v_rcp_f32_e32 v85, v85
	v_pk_mul_f32 v[86:87], v[100:101], v[90:91] op_sel_hi:[0,1]
	v_pk_mul_f32 v[80:81], v[80:81], v[86:87]
	s_nop 0
	v_cvt_pk_bf16_f32 v90, v80, v81
	v_pk_mul_f32 v[80:81], v[100:101], v[84:85] op_sel_hi:[0,1]
	v_pk_mul_f32 v[80:81], v[82:83], v[80:81]
	v_add_co_u32_e32 v84, vcc, s38, v114
	v_cvt_pk_bf16_f32 v91, v80, v81
	v_mul_f32_e32 v80, 0xbfb8aa3b, v167
	v_pk_mul_f32 v[82:83], v[76:77], v[80:81] op_sel_hi:[1,0]
	v_pk_mul_f32 v[76:77], v[78:79], v[80:81] op_sel_hi:[1,0]
	v_exp_f32_e32 v82, v82
	v_exp_f32_e32 v83, v83
	v_exp_f32_e32 v76, v76
	v_exp_f32_e32 v77, v77
	v_addc_co_u32_e32 v85, vcc, 0, v115, vcc
	v_pk_add_f32 v[82:83], v[82:83], 1.0 op_sel_hi:[1,0]
	v_pk_add_f32 v[76:77], v[76:77], 1.0 op_sel_hi:[1,0]
	v_rcp_f32_e32 v82, v82
	v_rcp_f32_e32 v83, v83
	v_rcp_f32_e32 v76, v76
	v_rcp_f32_e32 v77, v77
	global_store_dwordx4 v[84:85], v[88:91], off
	v_mul_f32_e32 v84, v167, v167
	v_pk_mul_f32 v[78:79], v[84:85], v[82:83] op_sel_hi:[0,1]
	v_pk_mul_f32 v[72:73], v[72:73], v[78:79]
	v_pk_mul_f32 v[78:79], v[68:69], v[80:81] op_sel_hi:[1,0]
	v_pk_mul_f32 v[76:77], v[84:85], v[76:77] op_sel_hi:[0,1]
	v_exp_f32_e32 v78, v78
	v_exp_f32_e32 v79, v79
	v_pk_mul_f32 v[74:75], v[74:75], v[76:77]
	v_pk_mul_f32 v[76:77], v[70:71], v[80:81] op_sel_hi:[1,0]
	v_cvt_pk_bf16_f32 v72, v72, v73
	v_cvt_pk_bf16_f32 v73, v74, v75
	v_pk_add_f32 v[74:75], v[78:79], 1.0 op_sel_hi:[1,0]
	v_exp_f32_e32 v76, v76
	v_exp_f32_e32 v77, v77
	v_rcp_f32_e32 v74, v74
	v_rcp_f32_e32 v75, v75
	v_pk_add_f32 v[68:69], v[76:77], 1.0 op_sel_hi:[1,0]
	s_nop 0
	v_rcp_f32_e32 v68, v68
	v_rcp_f32_e32 v69, v69
	v_pk_mul_f32 v[70:71], v[84:85], v[74:75] op_sel_hi:[0,1]
	v_pk_mul_f32 v[64:65], v[64:65], v[70:71]
	s_nop 0
	v_cvt_pk_bf16_f32 v74, v64, v65
	v_pk_mul_f32 v[64:65], v[84:85], v[68:69] op_sel_hi:[0,1]
	v_pk_mul_f32 v[64:65], v[66:67], v[64:65]
	v_and_b32_e32 v69, 0x1fcf, v146
	v_cvt_pk_bf16_f32 v75, v64, v65
	v_add_co_u32_e32 v64, vcc, s39, v114
	v_mul_f32_e32 v68, v168, v168
	s_nop 0
	v_addc_co_u32_e32 v65, vcc, 0, v115, vcc
	global_store_dwordx4 v[64:65], v[72:75], off offset:2048
	v_mul_f32_e32 v64, 0xbfb8aa3b, v168
	v_pk_mul_f32 v[66:67], v[60:61], v[64:65] op_sel_hi:[1,0]
	v_ashrrev_i32_e32 v65, 13, v146
	v_exp_f32_e32 v66, v66
	v_exp_f32_e32 v67, v67
	v_pk_mul_f32 v[60:61], v[62:63], v[64:65] op_sel_hi:[1,0]
	v_pk_add_f32 v[66:67], v[66:67], 1.0 op_sel_hi:[1,0]
	v_exp_f32_e32 v60, v60
	v_exp_f32_e32 v61, v61
	v_rcp_f32_e32 v66, v66
	v_rcp_f32_e32 v67, v67
	v_pk_add_f32 v[60:61], v[60:61], 1.0 op_sel_hi:[1,0]
	s_nop 0
	v_rcp_f32_e32 v60, v60
	v_rcp_f32_e32 v61, v61
	v_pk_mul_f32 v[62:63], v[68:69], v[66:67] op_sel_hi:[0,1]
	v_pk_mul_f32 v[56:57], v[56:57], v[62:63]
	v_pk_mul_f32 v[62:63], v[52:53], v[64:65] op_sel_hi:[1,0]
	v_pk_mul_f32 v[60:61], v[68:69], v[60:61] op_sel_hi:[0,1]
	v_exp_f32_e32 v62, v62
	v_exp_f32_e32 v63, v63
	v_pk_mul_f32 v[58:59], v[58:59], v[60:61]
	v_pk_mul_f32 v[60:61], v[54:55], v[64:65] op_sel_hi:[1,0]
	v_cvt_pk_bf16_f32 v56, v56, v57
	v_cvt_pk_bf16_f32 v57, v58, v59
	v_pk_add_f32 v[58:59], v[62:63], 1.0 op_sel_hi:[1,0]
	v_exp_f32_e32 v60, v60
	v_exp_f32_e32 v61, v61
	v_rcp_f32_e32 v58, v58
	v_rcp_f32_e32 v59, v59
; __device__ __forceinline__ unsigned cvt_pk_bf16(float lo, float hi) { unsigned r; asm volatile("v_cvt_pk_bf16_f32 %0, %1, %2" : "=v"(r) : "v"(lo), "v"(hi)); return r; }
; #define PG8_BAR __builtin_amdgcn_s_barrier()
;     __device__ __forceinline__ void operator()(const f32x4 (&acc)[2][2][4][2], const Unit& u, int wr, int wc, int fr, int fq) const {
;     ...
;         for (int ai = 0; ai < 2; ++ai)
; #pragma unroll
;             for (int m = 0; m < 4; ++m) {
;                 const int row = row0 + ai * HALF + m * 16; const float r = rs[ai][m];
;                 const float nrl = r * -1.44269504089f, r2 = r * r;
;                 unsigned pk[4];
; #pragma unroll
;                 for (int q = 0; q < 4; ++q) {
;                     const f32x4 ga = acc[ai][0][m][q >> 1], ua = acc[ai][1][m][q >> 1]; const int e0 = 2 * (q & 1);
;                     const f32x2 g = (f32x2){ga[e0], ga[e0 + 1]}, up = (f32x2){ua[e0], ua[e0 + 1]};
;                     const f32x2 t = g * nrl; f32x2 ex; ex.x = __builtin_amdgcn_exp2f(t.x); ex.y = __builtin_amdgcn_exp2f(t.y);
;                     const f32x2 d = ex + 1.0f; f32x2 rc; rc.x = __builtin_amdgcn_rcpf(d.x); rc.y = __builtin_amdgcn_rcpf(d.y);
;                     const f32x2 o = (g * up) * (rc * r2);
;                     pk[q] = cvt_pk_bf16(o.x, o.y);
;                 }
;                 u32x4 w; w.x = pk[0]; w.y = pk[1]; w.z = pk[2]; w.w = pk[3];
;                 *(u32x4*)(U + (size_t)(row >> 13) * U_SLAB + (size_t)(row & (SEQ - 1)) * U_PITCH + col0) = w;
; template <class Epi>
; __device__ __forceinline__ void gemm_phase(LAS unsigned char* lds, const Gemm g, const StaticOrder& S, const Epi& E) {
;     ...
;         if (wr == 0) PG8_BAR;
;         E(acc, cur, wr, wc, fr, fq);
;         if (!has_next) break;
; #pragma unroll
;         for (int a = 0; a < 2; ++a)
; #pragma unroll
;             for (int b = 0; b < 2; ++b)
; #pragma unroll
;                 for (int m = 0; m < 4; ++m)
; #pragma unroll
;                     for (int n = 0; n < 2; ++n) acc[a][b][m][n] = (f32x4){0.f, 0.f, 0.f, 0.f};
;         cur = nxt; cA = nA; cB = nB; ++ui;
;         if (wr == 1) PG8_BAR;
;     }
	v_pk_add_f32 v[52:53], v[60:61], 1.0 op_sel_hi:[1,0]
	s_nop 0
	v_rcp_f32_e32 v52, v52
	v_rcp_f32_e32 v53, v53
	v_pk_mul_f32 v[54:55], v[68:69], v[58:59] op_sel_hi:[0,1]
	v_pk_mul_f32 v[48:49], v[48:49], v[54:55]
	v_mul_f32_e32 v54, v160, v160
	v_cvt_pk_bf16_f32 v58, v48, v49
	v_pk_mul_f32 v[48:49], v[68:69], v[52:53] op_sel_hi:[0,1]
	v_pk_mul_f32 v[48:49], v[50:51], v[48:49]
	v_mul_u32_u24_e32 v50, 0xb40, v69
	v_lshlrev_b32_e32 v136, 1, v50
	v_mul_f32_e32 v50, 0xbfb8aa3b, v160
	v_pk_mul_f32 v[52:53], v[44:45], v[50:51] op_sel_hi:[1,0]
	v_pk_mul_f32 v[44:45], v[46:47], v[50:51] op_sel_hi:[1,0]
	v_exp_f32_e32 v52, v52
	v_exp_f32_e32 v53, v53
	v_exp_f32_e32 v44, v44
	v_exp_f32_e32 v45, v45
	v_cvt_pk_bf16_f32 v59, v48, v49
	v_pk_add_f32 v[52:53], v[52:53], 1.0 op_sel_hi:[1,0]
	v_mov_b64_e32 v[48:49], s[16:17]
	v_rcp_f32_e32 v52, v52
	v_rcp_f32_e32 v53, v53
	v_pk_add_f32 v[44:45], v[44:45], 1.0 op_sel_hi:[1,0]
	v_mad_i64_i32 v[48:49], s[2:3], v65, s37, v[48:49]
	v_rcp_f32_e32 v44, v44
	v_rcp_f32_e32 v45, v45
	v_pk_mul_f32 v[46:47], v[54:55], v[52:53] op_sel_hi:[0,1]
	v_pk_mul_f32 v[40:41], v[40:41], v[46:47]
	v_pk_mul_f32 v[46:47], v[36:37], v[50:51] op_sel_hi:[1,0]
	v_pk_mul_f32 v[44:45], v[54:55], v[44:45] op_sel_hi:[0,1]
	v_exp_f32_e32 v46, v46
	v_exp_f32_e32 v47, v47
	v_pk_mul_f32 v[42:43], v[42:43], v[44:45]
	v_pk_mul_f32 v[44:45], v[38:39], v[50:51] op_sel_hi:[1,0]
	v_lshl_add_u64 v[48:49], v[48:49], 0, v[136:137]
	v_exp_f32_e32 v44, v44
	v_exp_f32_e32 v45, v45
	v_lshl_add_u64 v[48:49], v[48:49], 0, v[112:113]
	global_store_dwordx4 v[48:49], v[56:59], off
	v_cvt_pk_bf16_f32 v40, v40, v41
	v_cvt_pk_bf16_f32 v41, v42, v43
	v_pk_add_f32 v[42:43], v[46:47], 1.0 op_sel_hi:[1,0]
	v_pk_add_f32 v[36:37], v[44:45], 1.0 op_sel_hi:[1,0]
	v_rcp_f32_e32 v42, v42
	v_rcp_f32_e32 v43, v43
	v_rcp_f32_e32 v36, v36
	v_rcp_f32_e32 v37, v37
	s_mov_b64 s[2:3], -1
	v_pk_mul_f32 v[38:39], v[54:55], v[42:43] op_sel_hi:[0,1]
	v_pk_mul_f32 v[32:33], v[32:33], v[38:39]
	s_nop 0
	v_cvt_pk_bf16_f32 v42, v32, v33
	v_pk_mul_f32 v[32:33], v[54:55], v[36:37] op_sel_hi:[0,1]
	v_pk_mul_f32 v[32:33], v[34:35], v[32:33]
	v_add_co_u32_e32 v36, vcc, s28, v48
	v_cvt_pk_bf16_f32 v43, v32, v33
	v_mul_f32_e32 v32, 0xbfb8aa3b, v159
	v_pk_mul_f32 v[34:35], v[28:29], v[32:33] op_sel_hi:[1,0]
	v_pk_mul_f32 v[28:29], v[30:31], v[32:33] op_sel_hi:[1,0]
	v_exp_f32_e32 v34, v34
	v_exp_f32_e32 v35, v35
	v_exp_f32_e32 v28, v28
	v_exp_f32_e32 v29, v29
	v_addc_co_u32_e32 v37, vcc, 0, v49, vcc
	v_pk_add_f32 v[34:35], v[34:35], 1.0 op_sel_hi:[1,0]
	v_pk_add_f32 v[28:29], v[28:29], 1.0 op_sel_hi:[1,0]
	v_rcp_f32_e32 v34, v34
	v_rcp_f32_e32 v35, v35
	v_rcp_f32_e32 v28, v28
	v_rcp_f32_e32 v29, v29
	global_store_dwordx4 v[36:37], v[40:43], off offset:2048
	v_mul_f32_e32 v36, v159, v159
	v_pk_mul_f32 v[30:31], v[36:37], v[34:35] op_sel_hi:[0,1]
	v_pk_mul_f32 v[24:25], v[24:25], v[30:31]
	v_pk_mul_f32 v[30:31], v[20:21], v[32:33] op_sel_hi:[1,0]
	v_pk_mul_f32 v[28:29], v[36:37], v[28:29] op_sel_hi:[0,1]
	v_exp_f32_e32 v30, v30
	v_exp_f32_e32 v31, v31
	v_pk_mul_f32 v[26:27], v[26:27], v[28:29]
	v_pk_mul_f32 v[28:29], v[22:23], v[32:33] op_sel_hi:[1,0]
	v_cvt_pk_bf16_f32 v24, v24, v25
	v_cvt_pk_bf16_f32 v25, v26, v27
	v_pk_add_f32 v[26:27], v[30:31], 1.0 op_sel_hi:[1,0]
	v_exp_f32_e32 v28, v28
	v_exp_f32_e32 v29, v29
	v_rcp_f32_e32 v26, v26
	v_rcp_f32_e32 v27, v27
	v_pk_add_f32 v[20:21], v[28:29], 1.0 op_sel_hi:[1,0]
	s_nop 0
	v_rcp_f32_e32 v20, v20
	v_rcp_f32_e32 v21, v21
	v_pk_mul_f32 v[22:23], v[36:37], v[26:27] op_sel_hi:[0,1]
	v_pk_mul_f32 v[16:17], v[16:17], v[22:23]
	s_nop 0
	v_cvt_pk_bf16_f32 v26, v16, v17
	v_pk_mul_f32 v[16:17], v[36:37], v[20:21] op_sel_hi:[0,1]
	v_pk_mul_f32 v[16:17], v[18:19], v[16:17]
	v_add_co_u32_e32 v20, vcc, s38, v48
	v_cvt_pk_bf16_f32 v27, v16, v17
	v_mul_f32_e32 v16, 0xbfb8aa3b, v147
	v_pk_mul_f32 v[18:19], v[12:13], v[16:17] op_sel_hi:[1,0]
	v_pk_mul_f32 v[12:13], v[14:15], v[16:17] op_sel_hi:[1,0]
	v_exp_f32_e32 v18, v18
	v_exp_f32_e32 v19, v19
	v_exp_f32_e32 v12, v12
	v_exp_f32_e32 v13, v13
	v_addc_co_u32_e32 v21, vcc, 0, v49, vcc
	v_pk_add_f32 v[18:19], v[18:19], 1.0 op_sel_hi:[1,0]
	v_pk_add_f32 v[12:13], v[12:13], 1.0 op_sel_hi:[1,0]
	v_rcp_f32_e32 v18, v18
	v_rcp_f32_e32 v19, v19
	v_rcp_f32_e32 v12, v12
	v_rcp_f32_e32 v13, v13
	global_store_dwordx4 v[20:21], v[24:27], off
	v_mul_f32_e32 v20, v147, v147
	v_pk_mul_f32 v[14:15], v[20:21], v[18:19] op_sel_hi:[0,1]
	v_pk_mul_f32 v[8:9], v[8:9], v[14:15]
	v_pk_mul_f32 v[14:15], v[4:5], v[16:17] op_sel_hi:[1,0]
	v_pk_mul_f32 v[12:13], v[20:21], v[12:13] op_sel_hi:[0,1]
	v_exp_f32_e32 v14, v14
	v_exp_f32_e32 v15, v15
	v_pk_mul_f32 v[10:11], v[10:11], v[12:13]
	v_pk_mul_f32 v[12:13], v[6:7], v[16:17] op_sel_hi:[1,0]
	v_cvt_pk_bf16_f32 v8, v8, v9
	v_cvt_pk_bf16_f32 v9, v10, v11
	v_pk_add_f32 v[10:11], v[14:15], 1.0 op_sel_hi:[1,0]
	v_exp_f32_e32 v12, v12
	v_exp_f32_e32 v13, v13
	v_rcp_f32_e32 v10, v10
	v_rcp_f32_e32 v11, v11
	v_pk_add_f32 v[4:5], v[12:13], 1.0 op_sel_hi:[1,0]
	s_nop 0
	v_rcp_f32_e32 v4, v4
	v_rcp_f32_e32 v5, v5
	v_pk_mul_f32 v[6:7], v[20:21], v[10:11] op_sel_hi:[0,1]
	v_pk_mul_f32 v[0:1], v[0:1], v[6:7]
	s_nop 0
	v_cvt_pk_bf16_f32 v10, v0, v1
	v_pk_mul_f32 v[0:1], v[20:21], v[4:5] op_sel_hi:[0,1]
	v_pk_mul_f32 v[0:1], v[2:3], v[0:1]
	s_nop 0
	v_cvt_pk_bf16_f32 v11, v0, v1
	v_add_co_u32_e32 v0, vcc, 0x43000, v48
	s_nop 1
	v_addc_co_u32_e32 v1, vcc, 0, v49, vcc
	s_andn2_b64 vcc, exec, s[4:5]
	global_store_dwordx4 v[0:1], v[8:11], off offset:2048
	s_cbranch_vccnz .LBB0_925
	s_andn2_b64 vcc, exec, s[0:1]
	s_cbranch_vccnz .LBB0_924
	s_barrier
	s_branch .LBB0_924
